# GEMM prologue de-serialisation: K-tile 1 staging DMAs issued before the first counted wait (vmcnt(2)->vmcnt(8), stagger and first barrier moved behind them), seven big GEMM prologues
# baseline (speedup 1.0000x reference)
; template <class Epi, class Sched, bool ALIGN_EPI = false, bool SP2 = false>
; __device__ __forceinline__ void gemm_phase(PG8_LAS unsigned char* lds, const Gemm g, const Sched& S, const Epi& E, const int tid) {
;     const int wid = __builtin_amdgcn_readfirstlane(tid >> 6), lane = tid & 63, wr = wid >> 2, wc = wid & 3, fr = lane & 15, fq = lane >> 4;
;     const int K = g.K, nt = K / BK;
;     unsigned voffA[2], voffB[2];
; #pragma unroll
;     for (int i = 0; i < 2; ++i) { int R, C; stage_rc(tid * 16 + i * 8192, R, C); const int Rb = Epi::PERM ? (2 * (R & ~31) + perm32(R & 31)) : R;
;         voffA[i] = (unsigned)(R * K + C) * 2u; voffB[i] = (unsigned)(Rb * K + C) * 2u; }
;     const size_t kstep = (size_t)(BK * 2);
;     const size_t hstep = (size_t)HALF * K * 2;
;     const size_t tstep = 2 * hstep;
;     const size_t hstepB = Epi::PERM ? (size_t)32 * K * 2 : hstep;
;     const unsigned ldsw = (unsigned)wid * 1024u;
;     const int aoff = lds_byte(wr * 64 + fr, fq * 8), boff = lds_byte(wc * 32 + fr, fq * 8);
;     ...
;     Unit cur, nxt; int ui = 0;
;     if (!S.next(0, cur)) return;
;     f32x4 acc[2][2][4][2];
;     u32x4 iw_[Epi::HAS_INIT ? 16 : 1];
;     if constexpr (Epi::HAS_INIT) E.init_issue(iw_, cur, wr, wc, fr, fq);
;     else {
; #pragma unroll
;     for (int a = 0; a < 2; ++a)
; #pragma unroll
;         for (int b = 0; b < 2; ++b)
; #pragma unroll
;             for (int m = 0; m < 4; ++m)
; #pragma unroll
;                 for (int n = 0; n < 2; ++n) acc[a][b][m][n] = (f32x4){0.f, 0.f, 0.f, 0.f};
;     }
;     bf16x8 At[4][2], B0[2][2], B1[2][2];
;     const char* cA = (const char*)g.A + (size_t)cur.pm * tstep; const char* cB = (const char*)g.Bt + (size_t)cur.pn * tstep;
;     S.a_ready(cur);
;     if constexpr (SP2) {
;         PG8_STAGE(PG8_SB(0, 0), cB, voffB); PG8_STAGE(PG8_SB(0, 1), cB + hstepB, voffB); PG8_STAGE(PG8_SA(0, 0), cA, voffA); PG8_STAGE(PG8_SA(0, 1), cA + hstep, voffA);
;         if (wr == 1) PG8_BAR;
;         PG8_WAIT_V(2); PG8_BAR;
;         PG8_STAGE(PG8_SB(1, 0), cB + kstep, voffB); PG8_STAGE(PG8_SA(1, 0), cA + kstep, voffA); PG8_STAGE(PG8_SB(1, 1), cB + hstepB + kstep, voffB);
;         PG8_WAIT_V(6); PG8_BAR;
;     } else {
;         PG8_STAGE(PG8_SB(0, 0), cB, voffB); PG8_STAGE(PG8_SA(0, 0), cA, voffA); PG8_STAGE(PG8_SB(0, 1), cB + hstepB, voffB); PG8_STAGE(PG8_SA(0, 1), cA + hstep, voffA);
;         if (wr == 1) PG8_BAR;
.LBB0_176:
	v_ashrrev_i32_e32 v3, 31, v133
	v_lshrrev_b32_e32 v3, 26, v3
	v_add_u32_e32 v3, v133, v3
	v_ashrrev_i32_e32 v4, 6, v3
	v_bfe_i32 v3, v133, 27, 1
	v_lshlrev_b32_e32 v7, 4, v133
	v_lshrrev_b32_e32 v3, 22, v3
	v_add_u32_e32 v3, v7, v3
	v_and_b32_e32 v3, 0xfffffc00, v3
	v_sub_u32_e32 v3, v7, v3
	v_lshrrev_b32_e32 v5, 4, v3
	v_bitop3_b32 v3, v5, v3, 32 bitop3:0x6c
	v_lshlrev_b32_e32 v5, 3, v4
	v_and_b32_e32 v6, -16, v5
	v_ashrrev_i32_e32 v5, 31, v3
	v_lshrrev_b32_e32 v5, 26, v5
	v_add_u32_e32 v8, v3, v5
	s_mul_i32 s6, s94, 0x680000
	v_ashrrev_i32_e32 v5, 6, v8
	s_mul_hi_u32 s5, s94, 0x680000
	s_add_u32 s6, s0, s6
	v_add_u32_e32 v158, v5, v6
	v_lshlrev_b32_e32 v6, 5, v4
	s_addc_u32 s5, s1, s5
	v_and_b32_e32 v9, 32, v6
	v_and_b32_e32 v6, 0xc0, v8
	s_add_u32 s12, s6, 0x6d00000
	v_sub_u32_e32 v3, v3, v6
	s_addc_u32 s13, s5, 0
	v_ashrrev_i16_sdwa v3, v205, sext(v3) dst_sel:DWORD dst_unused:UNUSED_PAD src0_sel:DWORD src1_sel:BYTE_0
	s_add_u32 s14, s0, 0xc300000
	v_bfe_i32 v6, v3, 0, 16
	v_lshrrev_b32_e32 v3, 2, v158
	s_addc_u32 s15, s1, 0
	v_and_b32_e32 v159, 4, v3
	v_and_b32_e32 v156, 15, v133
	v_lshrrev_b32_e32 v3, 1, v133
	s_add_u32 s6, s0, 0x1f900000
	v_add_u32_e32 v132, v9, v6
	v_lshlrev_b32_e32 v161, 1, v158
	v_and_b32_e32 v160, 3, v5
	v_and_b32_e32 v157, 24, v3
	v_lshlrev_b32_e32 v3, 6, v156
	s_addc_u32 s7, s1, 0
	s_andn2_b64 vcc, exec, s[16:17]
	s_cbranch_vccnz .LBB0_224
	v_and_b32_e32 v8, 0x1fffd8, v161
	v_or3_b32 v8, v160, v8, v159
	v_lshlrev_b32_e32 v9, 1, v132
	v_lshl_add_u32 v136, v8, 11, v9
	v_add_u32_e32 v8, 0x2000, v7
	v_ashrrev_i32_e32 v7, 31, v8
	v_lshrrev_b32_e32 v7, 22, v7
	v_add_u32_e32 v7, v8, v7
	v_ashrrev_i32_e32 v7, 10, v7
	v_lshl_add_u32 v134, v158, 11, v9
	v_mul_i32_i24_e32 v9, 0x400, v7
	v_sub_u32_e32 v8, v8, v9
	v_lshrrev_b32_e32 v9, 4, v8
	v_bitop3_b32 v9, v9, v8, 32 bitop3:0x6c
	v_lshlrev_b32_e32 v8, 3, v7
	v_and_b32_e32 v10, -16, v8
	v_ashrrev_i32_e32 v8, 31, v9
	v_lshrrev_b32_e32 v8, 26, v8
	s_ashr_i32 s18, s3, 6
	v_add_u32_e32 v11, v9, v8
	s_ashr_i32 s5, s4, 31
	s_ashr_i32 s37, s36, 31
	v_ashrrev_i32_e32 v8, 6, v11
	v_and_b32_e32 v11, 0xc0, v11
	s_ashr_i32 s20, s3, 8
	s_lshl_b32 s62, s18, 10
	s_lshl_b64 s[16:17], s[4:5], 19
	s_lshl_b64 s[22:23], s[36:37], 19
	v_add_u32_e32 v10, v8, v10
	v_sub_u32_e32 v9, v9, v11
	s_add_u32 s40, s12, s22
	v_lshlrev_b32_e32 v12, 5, v7
	v_ashrrev_i16_sdwa v9, v205, sext(v9) dst_sel:DWORD dst_unused:UNUSED_PAD src0_sel:DWORD src1_sel:BYTE_0
	v_lshlrev_b32_e32 v11, 1, v10
	v_lshrrev_b32_e32 v13, 2, v10
	s_addc_u32 s41, s13, s23
	s_add_i32 s63, s62, 0
	v_and_b32_e32 v12, 32, v12
	v_bfe_i32 v9, v9, 0, 16
	v_and_b32_e32 v13, 4, v13
	v_and_b32_e32 v14, 3, v8
	v_and_b32_e32 v11, 0x1fffd8, v11
	s_add_i32 m0, s63, 0x10000
	v_or3_b32 v11, v14, v13, v11
	v_add_lshl_u32 v12, v12, v9, 1
	global_load_lds_dwordx4 v136, s[40:41]
	s_add_i32 m0, s63, 0x12000
	v_lshl_add_u32 v140, v11, 11, v12
	s_add_u32 s22, s40, 0x10000
	global_load_lds_dwordx4 v140, s[40:41]
	s_addc_u32 s23, s41, 0
	s_add_i32 m0, s63, 0x14000
	v_lshl_add_u32 v138, v10, 11, v12
	global_load_lds_dwordx4 v136, s[22:23]
	s_add_i32 m0, s63, 0x16000
	s_add_u32 s38, s14, s16
	s_addc_u32 s39, s15, s17
	s_add_i32 s64, s63, 0x2000
	global_load_lds_dwordx4 v140, s[22:23]
	s_mov_b32 m0, s63
	s_add_u32 s16, s38, 0x40000
	global_load_lds_dwordx4 v134, s[38:39]
	s_mov_b32 m0, s64
	s_addc_u32 s17, s39, 0
	s_add_i32 s65, s63, 0x4000
	global_load_lds_dwordx4 v138, s[38:39]
	s_mov_b32 m0, s65
	s_add_i32 s76, s63, 0x6000
	global_load_lds_dwordx4 v134, s[16:17]
	s_mov_b32 m0, s76
	s_cmp_eq_u32 s20, 1
	global_load_lds_dwordx4 v138, s[16:17]
	s_cselect_b64 s[16:17], -1, 0
	s_cmp_lg_u32 s20, 1
	s_cbranch_scc1 .LBB0_179
	s_nop 0
.LBB0_179:
	v_mov_b32_e32 v137, v2
	v_lshl_add_u64 v[10:11], s[40:41], 0, v[136:137]
	v_mov_b32_e32 v141, v2
	v_lshlrev_b32_e32 v18, 1, v157
	v_lshlrev_b32_e32 v20, 2, v156
	v_lshl_add_u64 v[12:13], s[40:41], 0, v[140:141]
	v_mov_b32_e32 v135, v2
	s_and_b32 s5, s18, 3
	v_lshl_or_b32 v19, v156, 6, v18
	s_lshl_b32 s18, s20, 13
	v_and_b32_e32 v21, 32, v20
	s_add_i32 m0, s63, 0x18000
	v_lshl_add_u64 v[10:11], v[10:11], 0, s[52:53]
	v_lshl_add_u64 v[14:15], s[38:39], 0, v[134:135]
	v_mov_b32_e32 v139, v2
	v_bitop3_b32 v19, v19, s18, v21 bitop3:0xde
	v_or_b32_e32 v18, v18, v3
	s_lshl_b32 s18, s5, 12
	s_nop 0
	s_nop 0
	global_load_lds_dwordx4 v[10:11], off
	v_lshl_add_u64 v[10:11], v[12:13], 0, s[52:53]
	s_add_i32 m0, s63, 0x1a000
	s_add_i32 s78, s63, 0x8000
	s_add_i32 s79, s63, 0xa000
	v_lshl_add_u64 v[16:17], s[38:39], 0, v[138:139]
	v_bitop3_b32 v163, s18, v18, v21 bitop3:0xf6
	global_load_lds_dwordx4 v[10:11], off
	v_lshl_add_u64 v[10:11], v[14:15], 0, s[52:53]
	s_mov_b32 m0, s78
	s_add_u32 s18, s40, 0x10080
	global_load_lds_dwordx4 v[10:11], off
	v_lshl_add_u64 v[10:11], v[16:17], 0, s[52:53]
	s_mov_b32 m0, s79
	s_addc_u32 s19, s41, 0
	global_load_lds_dwordx4 v[10:11], off
	s_add_i32 m0, s63, 0x1c000
	v_lshl_add_u64 v[10:11], s[18:19], 0, v[136:137]
	global_load_lds_dwordx4 v[10:11], off
	v_lshl_add_u64 v[10:11], s[18:19], 0, v[140:141]
	s_add_i32 m0, s63, 0x1e000
	s_cmpk_lt_u32 s3, 0x100
	global_load_lds_dwordx4 v[10:11], off
	v_lshlrev_b32_e32 v10, 14, v4
	v_and_b32_e32 v10, 0xffff8000, v10
	v_lshl_add_u32 v5, v5, 11, v10
	v_and_b32_e32 v4, 1, v4
	v_lshl_or_b32 v4, v4, 6, v5
	v_lshl_add_u32 v142, v6, 1, v4
	v_lshlrev_b32_e32 v4, 14, v7
	s_cselect_b64 s[18:19], -1, 0
	s_lshl_b32 s3, s20, 8
	v_and_b32_e32 v4, 0xffff8000, v4
	s_cmp_lg_u32 s16, 0
	s_cbranch_scc0 .Lpd0
	s_barrier
.Lpd0:
	s_waitcnt vmcnt(8)
	s_barrier
	s_waitcnt vmcnt(6)
	s_add_i32 s3, s3, 0
	v_lshl_add_u32 v4, v8, 11, v4
	v_and_b32_e32 v5, 1, v7
	s_add_i32 s3, s3, 0x20000
	v_lshl_or_b32 v4, v5, 6, v4
	v_lshl_or_b32 v162, s20, 6, v156
	s_lshl_b32 s80, s54, 3
	v_add_u32_e32 v164, s3, v20
	v_lshl_or_b32 v165, s5, 6, v157
	v_mov_b32_e32 v143, v2
	v_lshl_add_u32 v144, v9, 1, v4
	v_mov_b32_e32 v145, v2
	s_mov_b32 s81, 0
	v_add_u32_e32 v166, 0, v19
	s_barrier
	s_branch .LBB0_182

; template <class Epi, class Sched, bool ALIGN_EPI = false, bool SP2 = false>
; __device__ __forceinline__ void gemm_phase(PG8_LAS unsigned char* lds, const Gemm g, const Sched& S, const Epi& E, const int tid) {
;     const int wid = __builtin_amdgcn_readfirstlane(tid >> 6), lane = tid & 63, wr = wid >> 2, wc = wid & 3, fr = lane & 15, fq = lane >> 4;
;     const int K = g.K, nt = K / BK;
;     unsigned voffA[2], voffB[2];
; #pragma unroll
;     for (int i = 0; i < 2; ++i) { int R, C; stage_rc(tid * 16 + i * 8192, R, C); const int Rb = Epi::PERM ? (2 * (R & ~31) + perm32(R & 31)) : R;
;         voffA[i] = (unsigned)(R * K + C) * 2u; voffB[i] = (unsigned)(Rb * K + C) * 2u; }
;     const size_t kstep = (size_t)(BK * 2);
;     const size_t hstep = (size_t)HALF * K * 2;
;     const size_t tstep = 2 * hstep;
;     const size_t hstepB = Epi::PERM ? (size_t)32 * K * 2 : hstep;
;     const unsigned ldsw = (unsigned)wid * 1024u;
;     const int aoff = lds_byte(wr * 64 + fr, fq * 8), boff = lds_byte(wc * 32 + fr, fq * 8);
;     ...
;     Unit cur, nxt; int ui = 0;
;     if (!S.next(0, cur)) return;
;     f32x4 acc[2][2][4][2];
;     u32x4 iw_[Epi::HAS_INIT ? 16 : 1];
;     if constexpr (Epi::HAS_INIT) E.init_issue(iw_, cur, wr, wc, fr, fq);
;     else {
; #pragma unroll
;     for (int a = 0; a < 2; ++a)
; #pragma unroll
;         for (int b = 0; b < 2; ++b)
; #pragma unroll
;             for (int m = 0; m < 4; ++m)
; #pragma unroll
;                 for (int n = 0; n < 2; ++n) acc[a][b][m][n] = (f32x4){0.f, 0.f, 0.f, 0.f};
;     }
;     bf16x8 At[4][2], B0[2][2], B1[2][2];
;     const char* cA = (const char*)g.A + (size_t)cur.pm * tstep; const char* cB = (const char*)g.Bt + (size_t)cur.pn * tstep;
;     S.a_ready(cur);
;     if constexpr (SP2) {
;         PG8_STAGE(PG8_SB(0, 0), cB, voffB); PG8_STAGE(PG8_SB(0, 1), cB + hstepB, voffB); PG8_STAGE(PG8_SA(0, 0), cA, voffA); PG8_STAGE(PG8_SA(0, 1), cA + hstep, voffA);
;         if (wr == 1) PG8_BAR;
;         PG8_WAIT_V(2); PG8_BAR;
;         PG8_STAGE(PG8_SB(1, 0), cB + kstep, voffB); PG8_STAGE(PG8_SA(1, 0), cA + kstep, voffA); PG8_STAGE(PG8_SB(1, 1), cB + hstepB + kstep, voffB);
;         PG8_WAIT_V(6); PG8_BAR;
;     } else {
;         PG8_STAGE(PG8_SB(0, 0), cB, voffB); PG8_STAGE(PG8_SA(0, 0), cA, voffA); PG8_STAGE(PG8_SB(0, 1), cB + hstepB, voffB); PG8_STAGE(PG8_SA(0, 1), cA + hstep, voffA);
;         if (wr == 1) PG8_BAR;
.LBB0_607:
	v_ashrrev_i32_e32 v5, 31, v3
	s_lshl_b64 s[0:1], s[94:95], 22
	v_lshrrev_b32_e32 v5, 26, v5
	s_add_u32 s0, s18, s0
	v_add_u32_e32 v5, v3, v5
	s_addc_u32 s1, s19, s1
	v_ashrrev_i32_e32 v12, 6, v5
	v_bfe_i32 v5, v3, 27, 1
	s_add_u32 s28, s0, 0x6100000
	v_lshlrev_b32_e32 v4, 4, v3
	v_lshrrev_b32_e32 v5, 22, v5
	s_addc_u32 s29, s1, 0
	v_add_u32_e32 v5, v4, v5
	s_add_u32 s24, s18, 0xc300000
	v_and_b32_e32 v5, 0xfffffc00, v5
	s_addc_u32 s25, s19, 0
	v_sub_u32_e32 v5, v4, v5
	s_add_u32 s0, s18, 0x10b00000
	v_lshrrev_b32_e32 v6, 4, v5
	s_addc_u32 s1, s19, 0
	v_bitop3_b32 v5, v6, v5, 32 bitop3:0x6c
	s_add_u32 s14, s18, 0x12d00000
	v_ashrrev_i32_e32 v7, 31, v5
	s_addc_u32 s15, s19, 0
	s_mul_i32 s9, s94, 0x18000
	v_lshrrev_b32_e32 v7, 26, v7
	s_mul_hi_u32 s7, s94, 0x18000
	s_add_u32 s9, s16, s9
	v_add_u32_e32 v7, v5, v7
	s_addc_u32 s7, s17, s7
	v_lshlrev_b32_e32 v6, 3, v12
	v_ashrrev_i32_e32 v13, 6, v7
	v_and_b32_e32 v7, 0xc0, v7
	s_add_u32 s18, s9, 0x8410000
	v_and_b32_e32 v6, -16, v6
	v_sub_u32_e32 v5, v5, v7
	s_addc_u32 s19, s7, 0
	s_mul_i32 s9, s94, 0x180000
	v_add_u32_e32 v133, v13, v6
	v_ashrrev_i16_sdwa v5, v205, sext(v5) dst_sel:DWORD dst_unused:UNUSED_PAD src0_sel:DWORD src1_sel:BYTE_0
	s_mul_hi_u32 s7, s94, 0x180000
	s_add_u32 s9, s16, s9
	v_lshlrev_b32_e32 v6, 5, v12
	v_bfe_i32 v14, v5, 0, 16
	v_lshrrev_b32_e32 v5, 2, v133
	s_addc_u32 s7, s17, s7
	v_and_b32_e32 v6, 32, v6
	v_and_b32_e32 v171, 4, v5
	v_lshrrev_b32_e32 v5, 1, v3
	s_add_u32 s20, s9, 0x8d40000
	v_add_u32_e32 v132, v6, v14
	v_lshlrev_b32_e32 v173, 1, v133
	v_and_b32_e32 v172, 3, v13
	v_and_b32_e32 v170, 15, v3
	s_addc_u32 s21, s7, 0
	s_andn2_b64 vcc, exec, s[4:5]
	v_and_b32_e32 v143, 24, v5
	s_cbranch_vccnz .LBB0_735
	v_and_b32_e32 v5, 0x1fffd8, v173
	v_or3_b32 v5, v172, v5, v171
	v_lshlrev_b32_e32 v6, 1, v132
	v_add_u32_e32 v4, 0x2000, v4
	v_lshl_add_u32 v136, v5, 11, v6
	v_ashrrev_i32_e32 v5, 31, v4
	v_lshrrev_b32_e32 v5, 22, v5
	v_add_u32_e32 v5, v4, v5
	v_ashrrev_i32_e32 v15, 10, v5
	v_mul_i32_i24_e32 v5, 0x400, v15
	v_sub_u32_e32 v4, v4, v5
	v_lshrrev_b32_e32 v5, 4, v4
	v_bitop3_b32 v4, v5, v4, 32 bitop3:0x6c
	v_lshl_add_u32 v134, v133, 11, v6
	v_ashrrev_i32_e32 v6, 31, v4
	v_lshrrev_b32_e32 v6, 26, v6
	v_add_u32_e32 v6, v4, v6
	s_ashr_i32 s4, s3, 6
	v_lshlrev_b32_e32 v5, 3, v15
	v_ashrrev_i32_e32 v16, 6, v6
	v_and_b32_e32 v6, 0xc0, v6
	s_ashr_i32 s9, s8, 31
	s_ashr_i32 s7, s6, 31
	v_and_b32_e32 v5, -16, v5
	v_sub_u32_e32 v4, v4, v6
	s_ashr_i32 s38, s3, 8
	s_lshl_b32 s63, s4, 10
	s_lshl_b64 s[10:11], s[8:9], 19
	s_lshl_b64 s[12:13], s[6:7], 19
	v_add_u32_e32 v5, v16, v5
	v_ashrrev_i16_sdwa v4, v205, sext(v4) dst_sel:DWORD dst_unused:UNUSED_PAD src0_sel:DWORD src1_sel:BYTE_0
	s_add_u32 s12, s28, s12
	v_lshlrev_b32_e32 v7, 5, v15
	v_bfe_i32 v17, v4, 0, 16
	v_lshlrev_b32_e32 v4, 1, v5
	v_lshrrev_b32_e32 v6, 2, v5
	s_addc_u32 s13, s29, s13
	s_add_i32 s64, s63, 0
	v_and_b32_e32 v7, 32, v7
	v_and_b32_e32 v6, 4, v6
	v_and_b32_e32 v8, 3, v16
	v_and_b32_e32 v4, 0x1fffd8, v4
	s_add_i32 m0, s64, 0x10000
	v_or3_b32 v4, v8, v6, v4
	v_add_lshl_u32 v6, v7, v17, 1
	global_load_lds_dwordx4 v136, s[12:13]
	s_add_i32 m0, s64, 0x12000
	v_lshl_add_u32 v140, v4, 11, v6
	s_add_u32 s30, s12, 0x10000
	global_load_lds_dwordx4 v140, s[12:13]
	s_addc_u32 s31, s13, 0
	s_add_i32 m0, s64, 0x14000
	v_lshl_add_u32 v138, v5, 11, v6
	global_load_lds_dwordx4 v136, s[30:31]
	s_add_i32 m0, s64, 0x16000
	s_add_u32 s10, s24, s10
	s_addc_u32 s11, s25, s11
	s_add_i32 s65, s64, 0x2000
	global_load_lds_dwordx4 v140, s[30:31]
	s_mov_b32 m0, s64
	s_add_u32 s30, s10, 0x40000
	global_load_lds_dwordx4 v134, s[10:11]
	s_mov_b32 m0, s65
	s_addc_u32 s31, s11, 0
	s_add_i32 s86, s64, 0x4000
	global_load_lds_dwordx4 v138, s[10:11]
	s_mov_b32 m0, s86
	s_add_i32 s87, s64, 0x6000
	global_load_lds_dwordx4 v134, s[30:31]
	s_mov_b32 m0, s87
	v_mov_b32_e32 v137, v2
	global_load_lds_dwordx4 v138, s[30:31]
	v_mov_b32_e32 v141, v2
	v_mov_b32_e32 v135, v2
	v_mov_b32_e32 v139, v2
	s_cmp_eq_u32 s38, 1
	v_lshl_add_u64 v[10:11], s[12:13], 0, v[136:137]
	v_lshl_add_u64 v[8:9], s[12:13], 0, v[140:141]
	v_lshl_add_u64 v[4:5], s[10:11], 0, v[134:135]
	s_cselect_b64 s[30:31], -1, 0
	s_cmp_lg_u32 s38, 1
	v_lshl_add_u64 v[6:7], s[10:11], 0, v[138:139]
	s_cbranch_scc1 .LBB0_610
	s_nop 0
.LBB0_610:
	v_lshlrev_b32_e32 v18, 1, v143
	v_lshlrev_b32_e32 v19, 2, v170
	s_and_b32 s7, s4, 3
	v_lshl_or_b32 v18, v170, 6, v18
	s_lshl_b32 s4, s38, 13
	v_and_b32_e32 v20, 32, v19
	s_add_i32 m0, s64, 0x18000
	v_lshl_add_u64 v[10:11], v[10:11], 0, s[52:53]
	s_lshl_b32 s92, s38, 6
	v_bitop3_b32 v21, v18, s4, v20 bitop3:0xde
	s_lshl_b32 s4, s7, 12
	s_nop 0
	s_nop 0
	global_load_lds_dwordx4 v[10:11], off
	v_lshl_add_u64 v[8:9], v[8:9], 0, s[52:53]
	s_add_i32 m0, s64, 0x1a000
	s_add_i32 s93, s64, 0x8000
	s_add_i32 s95, s64, 0xa000
	v_bitop3_b32 v174, s4, v18, v20 bitop3:0xf6
	global_load_lds_dwordx4 v[8:9], off
	v_lshl_add_u64 v[4:5], v[4:5], 0, s[52:53]
	s_mov_b32 m0, s93
	s_add_u32 s4, s12, 0x10080
	global_load_lds_dwordx4 v[4:5], off
	v_lshl_add_u64 v[4:5], v[6:7], 0, s[52:53]
	s_mov_b32 m0, s95
	s_addc_u32 s5, s13, 0
	global_load_lds_dwordx4 v[4:5], off
	s_add_i32 m0, s64, 0x1c000
	v_lshl_add_u64 v[4:5], s[4:5], 0, v[136:137]
	global_load_lds_dwordx4 v[4:5], off
	v_lshl_add_u64 v[4:5], s[4:5], 0, v[140:141]
	s_add_i32 m0, s64, 0x1e000
	s_cmpk_lt_u32 s3, 0x100
	global_load_lds_dwordx4 v[4:5], off
	v_and_b32_e32 v4, 7, v3
	v_subrev_co_u32_e64 v142, s[4:5], 5, v4
	v_lshlrev_b32_e32 v4, 14, v12
	v_and_b32_e32 v4, 0xffff8000, v4
	v_lshl_add_u32 v4, v13, 11, v4
	v_and_b32_e32 v5, 1, v12
	v_lshl_or_b32 v4, v5, 6, v4
	s_cselect_b64 s[36:37], -1, 0
	s_lshl_b32 s3, s38, 8
	v_lshl_add_u32 v144, v14, 1, v4
	v_lshlrev_b32_e32 v4, 14, v15
	s_add_i32 s3, s3, 0
	v_and_b32_e32 v4, 0xffff8000, v4
	s_cmp_lg_u32 s30, 0
	s_cbranch_scc0 .Lpd1
	s_barrier
.Lpd1:
	s_waitcnt vmcnt(8)
	s_barrier
	s_waitcnt vmcnt(6)
	s_lshl_b32 s27, s55, 3
	s_add_i32 s3, s3, 0x20000
	v_lshl_add_u32 v4, v16, 11, v4
	v_and_b32_e32 v5, 1, v15
	s_cmp_eq_u64 s[16:17], 0
	v_lshl_or_b32 v4, v5, 6, v4
	v_add_u32_e32 v175, s3, v19
	s_cselect_b64 s[38:39], -1, 0
	v_lshl_or_b32 v176, s7, 6, v143
	v_mov_b32_e32 v145, v2
	v_lshl_add_u32 v146, v17, 1, v4
	v_mov_b32_e32 v147, v2
	s_mov_b32 s76, 0
	v_add_u32_e32 v177, 0, v21
	s_barrier
	s_branch .LBB0_613

; template <class Epi, class Sched, bool ALIGN_EPI = false, bool SP2 = false>
; __device__ __forceinline__ void gemm_phase(PG8_LAS unsigned char* lds, const Gemm g, const Sched& S, const Epi& E, const int tid) {
;     const int wid = __builtin_amdgcn_readfirstlane(tid >> 6), lane = tid & 63, wr = wid >> 2, wc = wid & 3, fr = lane & 15, fq = lane >> 4;
;     const int K = g.K, nt = K / BK;
;     unsigned voffA[2], voffB[2];
; #pragma unroll
;     for (int i = 0; i < 2; ++i) { int R, C; stage_rc(tid * 16 + i * 8192, R, C); const int Rb = Epi::PERM ? (2 * (R & ~31) + perm32(R & 31)) : R;
;         voffA[i] = (unsigned)(R * K + C) * 2u; voffB[i] = (unsigned)(Rb * K + C) * 2u; }
;     const size_t kstep = (size_t)(BK * 2);
;     const size_t hstep = (size_t)HALF * K * 2;
;     const size_t tstep = 2 * hstep;
;     const size_t hstepB = Epi::PERM ? (size_t)32 * K * 2 : hstep;
;     const unsigned ldsw = (unsigned)wid * 1024u;
;     const int aoff = lds_byte(wr * 64 + fr, fq * 8), boff = lds_byte(wc * 32 + fr, fq * 8);
;     ...
;     Unit cur, nxt; int ui = 0;
;     if (!S.next(0, cur)) return;
;     f32x4 acc[2][2][4][2];
;     u32x4 iw_[Epi::HAS_INIT ? 16 : 1];
;     if constexpr (Epi::HAS_INIT) E.init_issue(iw_, cur, wr, wc, fr, fq);
;     else {
; #pragma unroll
;     for (int a = 0; a < 2; ++a)
; #pragma unroll
;         for (int b = 0; b < 2; ++b)
; #pragma unroll
;             for (int m = 0; m < 4; ++m)
; #pragma unroll
;                 for (int n = 0; n < 2; ++n) acc[a][b][m][n] = (f32x4){0.f, 0.f, 0.f, 0.f};
;     }
;     bf16x8 At[4][2], B0[2][2], B1[2][2];
;     const char* cA = (const char*)g.A + (size_t)cur.pm * tstep; const char* cB = (const char*)g.Bt + (size_t)cur.pn * tstep;
;     S.a_ready(cur);
;     if constexpr (SP2) {
;         PG8_STAGE(PG8_SB(0, 0), cB, voffB); PG8_STAGE(PG8_SB(0, 1), cB + hstepB, voffB); PG8_STAGE(PG8_SA(0, 0), cA, voffA); PG8_STAGE(PG8_SA(0, 1), cA + hstep, voffA);
;         if (wr == 1) PG8_BAR;
;         PG8_WAIT_V(2); PG8_BAR;
;         PG8_STAGE(PG8_SB(1, 0), cB + kstep, voffB); PG8_STAGE(PG8_SA(1, 0), cA + kstep, voffA); PG8_STAGE(PG8_SB(1, 1), cB + hstepB + kstep, voffB);
;         PG8_WAIT_V(6); PG8_BAR;
;     } else {
;         PG8_STAGE(PG8_SB(0, 0), cB, voffB); PG8_STAGE(PG8_SA(0, 0), cA, voffA); PG8_STAGE(PG8_SB(0, 1), cB + hstepB, voffB); PG8_STAGE(PG8_SA(0, 1), cA + hstep, voffA);
;         if (wr == 1) PG8_BAR;
.LBB0_970:
	v_ashrrev_i32_e32 v5, 31, v3
	v_lshrrev_b32_e32 v5, 26, v5
	v_add_u32_e32 v5, v3, v5
	s_waitcnt vmcnt(0)
	v_ashrrev_i32_e32 v142, 6, v5
	v_bfe_i32 v5, v3, 27, 1
	v_lshlrev_b32_e32 v4, 4, v3
	v_lshrrev_b32_e32 v5, 22, v5
	v_add_u32_e32 v5, v4, v5
	v_and_b32_e32 v5, 0xfffffc00, v5
	s_ashr_i32 s42, s14, 6
	v_sub_u32_e32 v5, v4, v5
	s_waitcnt lgkmcnt(0)
	s_add_u32 s0, s12, s0
	v_lshrrev_b32_e32 v6, 4, v5
	s_addc_u32 s1, s13, s1
	s_lshl_b32 s6, s94, 21
	v_bitop3_b32 v5, v6, v5, 32 bitop3:0x6c
	s_add_u32 s10, s0, s6
	v_ashrrev_i32_e32 v7, 31, v5
	s_addc_u32 s11, s1, 0
	v_lshrrev_b32_e32 v7, 26, v7
	s_add_u32 s6, s12, 0x14f00000
	v_add_u32_e32 v7, v5, v7
	s_addc_u32 s7, s13, 0
	v_lshlrev_b32_e32 v6, 3, v142
	v_ashrrev_i32_e32 v143, 6, v7
	v_and_b32_e32 v7, 0xc0, v7
	s_add_u32 s8, s12, 0xc300000
	v_and_b32_e32 v6, -16, v6
	v_sub_u32_e32 v5, v5, v7
	s_addc_u32 s9, s13, 0
	v_add_u32_e32 v133, v143, v6
	v_lshlrev_b32_e32 v6, 5, v142
	v_ashrrev_i16_sdwa v5, v205, sext(v5) dst_sel:DWORD dst_unused:UNUSED_PAD src0_sel:DWORD src1_sel:BYTE_0
	s_add_u32 s0, s12, 0x2e200000
	v_and_b32_e32 v6, 32, v6
	v_bfe_i32 v144, v5, 0, 16
	v_lshrrev_b32_e32 v5, 2, v133
	v_readlane_b32 s88, v250, 8
	s_addc_u32 s1, s13, 0
	v_add_u32_e32 v132, v6, v144
	v_lshlrev_b32_e32 v155, 1, v133
	v_and_b32_e32 v153, 4, v5
	v_and_b32_e32 v154, 3, v143
	v_and_b32_e32 v152, 15, v3
	s_andn2_b64 vcc, exec, s[4:5]
	s_lshl_b32 s43, s42, 10
	v_readlane_b32 s89, v250, 9
	s_cbranch_vccnz .LBB0_1018
	v_and_b32_e32 v5, 0x1fffd8, v155
	v_or3_b32 v5, v154, v5, v153
	v_lshlrev_b32_e32 v6, 1, v132
	v_add_u32_e32 v4, 0x2000, v4
	v_lshl_add_u32 v136, v5, 11, v6
	v_ashrrev_i32_e32 v5, 31, v4
	v_lshrrev_b32_e32 v5, 22, v5
	v_add_u32_e32 v5, v4, v5
	v_ashrrev_i32_e32 v145, 10, v5
	v_mul_i32_i24_e32 v5, 0x400, v145
	v_sub_u32_e32 v4, v4, v5
	v_lshrrev_b32_e32 v5, 4, v4
	v_bitop3_b32 v4, v5, v4, 32 bitop3:0x6c
	v_lshl_add_u32 v134, v133, 11, v6
	v_ashrrev_i32_e32 v6, 31, v4
	v_lshrrev_b32_e32 v6, 26, v6
	v_add_u32_e32 v6, v4, v6
	v_lshlrev_b32_e32 v5, 3, v145
	v_ashrrev_i32_e32 v147, 6, v6
	v_and_b32_e32 v6, 0xc0, v6
	v_and_b32_e32 v5, -16, v5
	v_sub_u32_e32 v4, v4, v6
	v_add_u32_e32 v5, v147, v5
	v_ashrrev_i16_sdwa v4, v205, sext(v4) dst_sel:DWORD dst_unused:UNUSED_PAD src0_sel:DWORD src1_sel:BYTE_0
	v_lshlrev_b32_e32 v7, 5, v145
	v_bfe_i32 v148, v4, 0, 16
	v_lshlrev_b32_e32 v4, 1, v5
	v_lshrrev_b32_e32 v6, 2, v5
	s_ashr_i32 s5, s14, 8
	v_and_b32_e32 v7, 32, v7
	v_and_b32_e32 v6, 4, v6
	v_and_b32_e32 v8, 3, v147
	v_and_b32_e32 v4, 0x1fffd8, v4
	s_lshl_b32 s15, s5, 6
	s_lshl_b32 s12, s28, 8
	s_and_b32 s4, s42, 3
	v_or3_b32 v4, v8, v6, v4
	v_add_lshl_u32 v6, v7, v148, 1
	s_add_i32 s12, s12, s15
	v_bfe_u32 v146, v3, 4, 2
	v_lshl_add_u32 v140, v4, 11, v6
	v_or_b32_e32 v4, s12, v152
	s_lshl_b32 s12, s24, 8
	s_lshl_b32 s54, s4, 6
	v_lshlrev_b32_e32 v156, 3, v146
	s_or_b32 s12, s12, s54
	v_or_b32_e32 v10, 16, v4
	v_lshl_add_u32 v138, v5, 11, v6
	v_or_b32_e32 v6, s12, v156
	v_ashrrev_i32_e32 v5, 31, v4
	v_ashrrev_i32_e32 v11, 31, v10
	v_lshlrev_b64 v[8:9], 11, v[4:5]
	v_ashrrev_i32_e32 v7, 31, v6
	v_lshlrev_b64 v[10:11], 11, v[10:11]
	v_lshl_add_u64 v[8:9], s[8:9], 0, v[8:9]
	v_lshlrev_b64 v[6:7], 1, v[6:7]
	v_lshl_add_u64 v[10:11], s[8:9], 0, v[10:11]
	v_lshl_add_u64 v[8:9], v[8:9], 0, v[6:7]
	v_lshl_add_u64 v[10:11], v[10:11], 0, v[6:7]
	global_load_dwordx4 v[64:67], v[8:9], off
	global_load_dwordx4 v[56:59], v[8:9], off offset:64
	global_load_dwordx4 v[60:63], v[10:11], off
	global_load_dwordx4 v[48:51], v[10:11], off offset:64
	v_or_b32_e32 v10, 32, v4
	v_or_b32_e32 v4, 48, v4
	v_ashrrev_i32_e32 v11, 31, v10
	v_ashrrev_i32_e32 v5, 31, v4
	v_lshlrev_b64 v[10:11], 11, v[10:11]
	v_lshlrev_b64 v[4:5], 11, v[4:5]
	v_lshl_add_u64 v[10:11], s[8:9], 0, v[10:11]
	v_lshl_add_u64 v[4:5], s[8:9], 0, v[4:5]
	v_lshl_add_u64 v[10:11], v[10:11], 0, v[6:7]
	v_lshl_add_u64 v[4:5], v[4:5], 0, v[6:7]
	v_add_co_u32_e32 v6, vcc, s57, v8
	global_load_dwordx4 v[52:55], v[10:11], off
	global_load_dwordx4 v[40:43], v[10:11], off offset:64
	v_addc_co_u32_e32 v7, vcc, 0, v9, vcc
	global_load_dwordx4 v[44:47], v[4:5], off
	global_load_dwordx4 v[36:39], v[4:5], off offset:64
	v_lshl_add_u64 v[4:5], v[8:9], 0, s[50:51]
	global_load_dwordx4 v[32:35], v[6:7], off
	global_load_dwordx4 v[28:31], v[4:5], off offset:64
	v_add_co_u32_e32 v6, vcc, s26, v8
	s_mov_b32 s12, 0x50000
	s_nop 0
	v_addc_co_u32_e32 v7, vcc, 0, v9, vcc
	v_lshl_add_u64 v[4:5], v[8:9], 0, s[72:73]
	global_load_dwordx4 v[24:27], v[6:7], off
	global_load_dwordx4 v[20:23], v[4:5], off offset:64
	v_add_co_u32_e32 v6, vcc, s12, v8
	s_mov_b64 s[12:13], 0x58000
	s_nop 0
	v_addc_co_u32_e32 v7, vcc, 0, v9, vcc
	v_lshl_add_u64 v[16:17], v[8:9], 0, s[12:13]
	s_mov_b32 s12, 0x58000
	s_ashr_i32 s29, s28, 31
	s_ashr_i32 s25, s24, 31
	v_lshl_add_u64 v[4:5], v[8:9], 0, s[74:75]
	v_add_co_u32_e32 v8, vcc, s12, v8
	s_lshl_b64 s[12:13], s[28:29], 19
	s_lshl_b64 s[16:17], s[24:25], 19
	s_add_u32 s36, s10, s16
	s_addc_u32 s37, s11, s17
	s_add_i32 s29, s43, 0
	v_addc_co_u32_e32 v9, vcc, 0, v9, vcc
	s_add_i32 m0, s29, 0x10000
	global_load_dwordx4 v[12:15], v[6:7], off
	s_nop 0
	global_load_dwordx4 v[4:7], v[4:5], off offset:64
	s_nop 0
	global_load_dwordx4 v[8:11], v[8:9], off
	s_nop 0
	global_load_dwordx4 v[16:19], v[16:17], off offset:64
	v_mov_b32_e32 v137, v2
	global_load_lds_dwordx4 v136, s[36:37]
	s_add_i32 m0, s29, 0x12000
	s_add_u32 s16, s36, 0x10000
	global_load_lds_dwordx4 v140, s[36:37]
	s_addc_u32 s17, s37, 0
	s_add_i32 m0, s29, 0x14000
	v_mov_b32_e32 v141, v2
	global_load_lds_dwordx4 v136, s[16:17]
	s_add_i32 m0, s29, 0x16000
	s_add_u32 s38, s6, s12
	s_addc_u32 s39, s7, s13
	s_add_i32 s55, s29, 0x2000
	global_load_lds_dwordx4 v140, s[16:17]
	s_mov_b32 m0, s29
	s_add_u32 s12, s38, 0x40000
	global_load_lds_dwordx4 v134, s[38:39]
	s_mov_b32 m0, s55
	s_addc_u32 s13, s39, 0
	s_add_i32 s62, s29, 0x4000
	global_load_lds_dwordx4 v138, s[38:39]
	s_mov_b32 m0, s62
	s_add_i32 s63, s29, 0x6000
	global_load_lds_dwordx4 v134, s[12:13]
	s_mov_b32 m0, s63
	v_mov_b32_e32 v135, v2
	global_load_lds_dwordx4 v138, s[12:13]
	v_mov_b32_e32 v139, v2
	s_cmp_eq_u32 s5, 1
	v_lshl_add_u64 v[74:75], s[36:37], 0, v[136:137]
	v_lshl_add_u64 v[72:73], s[36:37], 0, v[140:141]
	v_lshl_add_u64 v[68:69], s[38:39], 0, v[134:135]
	s_cselect_b64 s[12:13], -1, 0
	s_cmp_lg_u32 s5, 1
	v_lshl_add_u64 v[70:71], s[38:39], 0, v[138:139]
	s_cbranch_scc1 .LBB0_973
	s_nop 0
; DI float bf_lo(unsigned u) { return __uint_as_float(u << 16); }
; DI float bf_hi(unsigned u) { return __uint_as_float(u & 0xffff0000u); }
; #define PG8_STAGE(bufoff, gbase, voff) do { _Pragma("unroll") for (int _i = 0; _i < 2; ++_i) \
;         __builtin_amdgcn_global_load_lds((const unsigned*)((const char*)(gbase) + (voff)[_i]), (PG8_LAS unsigned*)(lds + (bufoff) + ldsw + _i * 8192), 16, 0, 0); } while (0)
; #define PG8_WAIT_V(n) asm volatile("s_waitcnt vmcnt(" #n ")" ::: "memory")
; #define PG8_BAR __builtin_amdgcn_s_barrier()
;     DI void init_finish(f32x4 (&acc)[2][2][4][2], const u32x4 (&w)[R8::HAS_PRE ? 16 : 1]) const {
;         if constexpr (R8::HAS_PRE) {
; #pragma unroll
;             for (int ai = 0; ai < 2; ++ai)
; #pragma unroll
;                 for (int m = 0; m < 4; ++m)
; #pragma unroll
;                     for (int bj = 0; bj < 2; ++bj) { const u32x4 v = w[(ai * 4 + m) * 2 + bj];
;                         acc[ai][bj][m][0] = (f32x4){bf_lo(v.x), bf_hi(v.x), bf_lo(v.y), bf_hi(v.y)}; acc[ai][bj][m][1] = (f32x4){bf_lo(v.z), bf_hi(v.z), bf_lo(v.w), bf_hi(v.w)}; }
;         }
;     }
; template <class Epi, class Sched, bool ALIGN_EPI = false, bool SP2 = false>
; __device__ __forceinline__ void gemm_phase(PG8_LAS unsigned char* lds, const Gemm g, const Sched& S, const Epi& E, const int tid) {
;     ...
;         PG8_STAGE(PG8_SB(1, 0), cB + kstep, voffB); PG8_STAGE(PG8_SA(1, 0), cA + kstep, voffA); PG8_STAGE(PG8_SB(1, 1), cB + hstepB + kstep, voffB);
;         PG8_WAIT_V(6); PG8_BAR;
;     } else {
;         PG8_STAGE(PG8_SB(0, 0), cB, voffB); PG8_STAGE(PG8_SA(0, 0), cA, voffA); PG8_STAGE(PG8_SB(0, 1), cB + hstepB, voffB); PG8_STAGE(PG8_SA(0, 1), cA + hstep, voffA);
;         if (wr == 1) PG8_BAR;
;         PG8_WAIT_V(4); PG8_BAR;
;         PG8_STAGE(PG8_SB(1, 0), cB + kstep, voffB); PG8_STAGE(PG8_SA(1, 0), cA + kstep, voffA); PG8_STAGE(PG8_SB(1, 1), cB + hstepB + kstep, voffB);
;         PG8_WAIT_V(6); PG8_BAR;
;     }
;     if constexpr (Epi::HAS_INIT) E.init_finish(acc, iw_);
.LBB0_973:
	v_or_b32_e32 v157, s15, v152
	v_lshlrev_b32_e32 v76, 6, v157
	v_lshlrev_b32_e32 v77, 4, v146
	s_movk_i32 s15, 0x3c0
	v_lshlrev_b32_e32 v78, 2, v157
	v_and_or_b32 v76, v76, s15, v77
	s_lshl_b32 s5, s5, 13
	v_and_b32_e32 v78, 32, v78
	v_bitop3_b32 v149, v76, s5, v78 bitop3:0xde
	v_lshl_or_b32 v76, v152, 6, v77
	v_lshlrev_b32_e32 v77, 2, v152
	s_add_i32 m0, s29, 0x18000
	v_lshl_add_u64 v[74:75], v[74:75], 0, s[52:53]
	s_lshl_b32 s4, s4, 12
	v_and_b32_e32 v77, 32, v77
	s_nop 0
	s_nop 0
	global_load_lds_dwordx4 v[74:75], off
	v_lshl_add_u64 v[72:73], v[72:73], 0, s[52:53]
	s_add_i32 m0, s29, 0x1a000
	s_add_i32 s64, s29, 0x8000
	s_add_i32 s65, s29, 0xa000
	v_bitop3_b32 v158, s4, v76, v77 bitop3:0xf6
	global_load_lds_dwordx4 v[72:73], off
	v_lshl_add_u64 v[68:69], v[68:69], 0, s[52:53]
	s_mov_b32 m0, s64
	s_add_u32 s4, s36, 0x10080
	global_load_lds_dwordx4 v[68:69], off
	v_lshl_add_u64 v[68:69], v[70:71], 0, s[52:53]
	s_mov_b32 m0, s65
	s_addc_u32 s5, s37, 0
	global_load_lds_dwordx4 v[68:69], off
	s_add_i32 m0, s29, 0x1c000
	v_lshl_add_u64 v[68:69], s[4:5], 0, v[136:137]
	global_load_lds_dwordx4 v[68:69], off
	v_lshl_add_u64 v[68:69], s[4:5], 0, v[140:141]
	s_add_i32 m0, s29, 0x1e000
	v_cmp_eq_u32_e64 s[4:5], 0, v146
	global_load_lds_dwordx4 v[68:69], off
	v_lshlrev_b32_e32 v146, 14, v142
	v_and_b32_e32 v146, 0xffff8000, v146
	v_lshl_add_u32 v143, v143, 11, v146
	v_and_b32_e32 v142, 1, v142
	v_lshl_or_b32 v142, v142, 6, v143
	v_lshl_add_u32 v142, v144, 1, v142
	v_lshlrev_b32_e32 v144, 14, v145
	v_and_b32_e32 v144, 0xffff8000, v144
	s_cmp_lg_u32 s12, 0
	s_cbranch_scc0 .Lpd2
	s_barrier
.Lpd2:
	s_waitcnt vmcnt(8)
	s_barrier
	s_waitcnt vmcnt(6)
	v_lshl_add_u32 v144, v147, 11, v144
	v_and_b32_e32 v145, 1, v145
	s_cmpk_lt_u32 s14, 0x100
	v_lshl_or_b32 v144, v145, 6, v144
	s_waitcnt vmcnt(0)
	v_lshlrev_b32_e32 v120, 16, v64
	v_and_b32_e32 v121, 0xffff0000, v64
	v_lshlrev_b32_e32 v122, 16, v65
	v_and_b32_e32 v123, 0xffff0000, v65
	v_lshlrev_b32_e32 v128, 16, v66
	v_and_b32_e32 v129, 0xffff0000, v66
	v_lshlrev_b32_e32 v130, 16, v67
	v_and_b32_e32 v131, 0xffff0000, v67
	v_lshlrev_b32_e32 v116, 16, v56
	v_and_b32_e32 v117, 0xffff0000, v56
	v_lshlrev_b32_e32 v118, 16, v57
	v_and_b32_e32 v119, 0xffff0000, v57
	v_lshlrev_b32_e32 v124, 16, v58
	v_and_b32_e32 v125, 0xffff0000, v58
	v_lshlrev_b32_e32 v126, 16, v59
	v_and_b32_e32 v127, 0xffff0000, v59
	v_lshlrev_b32_e32 v100, 16, v60
	v_and_b32_e32 v101, 0xffff0000, v60
	v_lshlrev_b32_e32 v102, 16, v61
	v_and_b32_e32 v103, 0xffff0000, v61
	v_lshlrev_b32_e32 v108, 16, v62
	v_and_b32_e32 v109, 0xffff0000, v62
	v_lshlrev_b32_e32 v110, 16, v63
	v_and_b32_e32 v111, 0xffff0000, v63
	v_lshlrev_b32_e32 v104, 16, v48
	v_and_b32_e32 v105, 0xffff0000, v48
	v_lshlrev_b32_e32 v106, 16, v49
	v_and_b32_e32 v107, 0xffff0000, v49
	v_lshlrev_b32_e32 v112, 16, v50
	v_and_b32_e32 v113, 0xffff0000, v50
	v_lshlrev_b32_e32 v114, 16, v51
	v_and_b32_e32 v115, 0xffff0000, v51
	v_lshlrev_b32_e32 v84, 16, v52
	v_and_b32_e32 v85, 0xffff0000, v52
	v_lshlrev_b32_e32 v86, 16, v53
	v_and_b32_e32 v87, 0xffff0000, v53
	v_lshlrev_b32_e32 v92, 16, v54
	v_and_b32_e32 v93, 0xffff0000, v54
	v_lshlrev_b32_e32 v94, 16, v55
	v_and_b32_e32 v95, 0xffff0000, v55
	v_lshlrev_b32_e32 v88, 16, v40
	v_and_b32_e32 v89, 0xffff0000, v40
	v_lshlrev_b32_e32 v90, 16, v41
	v_and_b32_e32 v91, 0xffff0000, v41
	v_lshlrev_b32_e32 v96, 16, v42
	v_and_b32_e32 v97, 0xffff0000, v42
	v_lshlrev_b32_e32 v98, 16, v43
	v_and_b32_e32 v99, 0xffff0000, v43
	v_lshlrev_b32_e32 v68, 16, v44
	v_and_b32_e32 v69, 0xffff0000, v44
	v_lshlrev_b32_e32 v70, 16, v45
	v_and_b32_e32 v71, 0xffff0000, v45
	v_lshlrev_b32_e32 v76, 16, v46
	v_and_b32_e32 v77, 0xffff0000, v46
	v_lshlrev_b32_e32 v78, 16, v47
	v_and_b32_e32 v79, 0xffff0000, v47
	v_lshlrev_b32_e32 v72, 16, v36
	v_and_b32_e32 v73, 0xffff0000, v36
	v_lshlrev_b32_e32 v74, 16, v37
	v_and_b32_e32 v75, 0xffff0000, v37
	v_lshlrev_b32_e32 v80, 16, v38
	v_and_b32_e32 v81, 0xffff0000, v38
	v_lshlrev_b32_e32 v82, 16, v39
	v_and_b32_e32 v83, 0xffff0000, v39
	v_lshlrev_b32_e32 v52, 16, v32
	v_and_b32_e32 v53, 0xffff0000, v32
	v_lshlrev_b32_e32 v54, 16, v33
	v_and_b32_e32 v55, 0xffff0000, v33
	v_lshlrev_b32_e32 v60, 16, v34
	v_and_b32_e32 v61, 0xffff0000, v34
	v_lshlrev_b32_e32 v62, 16, v35
	v_and_b32_e32 v63, 0xffff0000, v35
	v_lshlrev_b32_e32 v56, 16, v28
	v_and_b32_e32 v57, 0xffff0000, v28
	v_lshlrev_b32_e32 v58, 16, v29
	v_and_b32_e32 v59, 0xffff0000, v29
	v_lshlrev_b32_e32 v64, 16, v30
	v_and_b32_e32 v65, 0xffff0000, v30
	v_lshlrev_b32_e32 v66, 16, v31
	v_and_b32_e32 v67, 0xffff0000, v31
	v_lshlrev_b32_e32 v36, 16, v24
	v_and_b32_e32 v37, 0xffff0000, v24
	v_lshlrev_b32_e32 v38, 16, v25
	v_and_b32_e32 v39, 0xffff0000, v25
	v_lshlrev_b32_e32 v44, 16, v26
	v_and_b32_e32 v45, 0xffff0000, v26
	v_lshlrev_b32_e32 v46, 16, v27
	v_and_b32_e32 v47, 0xffff0000, v27
	v_lshlrev_b32_e32 v40, 16, v20
	v_and_b32_e32 v41, 0xffff0000, v20
	v_lshlrev_b32_e32 v42, 16, v21
	v_and_b32_e32 v43, 0xffff0000, v21
	v_lshlrev_b32_e32 v48, 16, v22
	v_and_b32_e32 v49, 0xffff0000, v22
	v_lshlrev_b32_e32 v50, 16, v23
	v_and_b32_e32 v51, 0xffff0000, v23
	v_lshlrev_b32_e32 v20, 16, v12
	v_and_b32_e32 v21, 0xffff0000, v12
	v_lshlrev_b32_e32 v22, 16, v13
	v_and_b32_e32 v23, 0xffff0000, v13
	v_lshlrev_b32_e32 v28, 16, v14
	v_and_b32_e32 v29, 0xffff0000, v14
	v_lshlrev_b32_e32 v30, 16, v15
	v_and_b32_e32 v31, 0xffff0000, v15
	v_lshlrev_b32_e32 v24, 16, v4
	v_and_b32_e32 v25, 0xffff0000, v4
	v_lshlrev_b32_e32 v26, 16, v5
	v_and_b32_e32 v27, 0xffff0000, v5
	v_lshlrev_b32_e32 v32, 16, v6
	v_and_b32_e32 v33, 0xffff0000, v6
	v_lshlrev_b32_e32 v34, 16, v7
	v_and_b32_e32 v35, 0xffff0000, v7
	v_lshlrev_b32_e32 v4, 16, v8
	v_and_b32_e32 v5, 0xffff0000, v8
	v_lshlrev_b32_e32 v6, 16, v9
	v_and_b32_e32 v7, 0xffff0000, v9
	v_lshlrev_b32_e32 v12, 16, v10
	v_and_b32_e32 v13, 0xffff0000, v10
	v_lshlrev_b32_e32 v14, 16, v11
	v_and_b32_e32 v15, 0xffff0000, v11
	v_lshlrev_b32_e32 v8, 16, v16
	v_and_b32_e32 v9, 0xffff0000, v16
	v_lshlrev_b32_e32 v10, 16, v17
	v_and_b32_e32 v11, 0xffff0000, v17
	v_lshlrev_b32_e32 v16, 16, v18
	v_and_b32_e32 v17, 0xffff0000, v18
	v_lshlrev_b32_e32 v18, 16, v19
	v_and_b32_e32 v19, 0xffff0000, v19
	s_cselect_b64 s[14:15], -1, 0
	s_mov_b32 s66, 0
	s_lshl_b32 s67, s27, 3
	v_or_b32_e32 v159, s54, v156
	v_mov_b32_e32 v143, v2
	v_lshl_add_u32 v144, v148, 1, v144
	v_mov_b32_e32 v145, v2
	v_add_u32_e32 v160, 0, v149
	s_barrier
	s_branch .LBB0_976

; template <class Epi, class Sched, bool ALIGN_EPI = false, bool SP2 = false>
; __device__ __forceinline__ void gemm_phase(PG8_LAS unsigned char* lds, const Gemm g, const Sched& S, const Epi& E, const int tid) {
;     const int wid = __builtin_amdgcn_readfirstlane(tid >> 6), lane = tid & 63, wr = wid >> 2, wc = wid & 3, fr = lane & 15, fq = lane >> 4;
;     const int K = g.K, nt = K / BK;
;     unsigned voffA[2], voffB[2];
; #pragma unroll
;     for (int i = 0; i < 2; ++i) { int R, C; stage_rc(tid * 16 + i * 8192, R, C); const int Rb = Epi::PERM ? (2 * (R & ~31) + perm32(R & 31)) : R;
;         voffA[i] = (unsigned)(R * K + C) * 2u; voffB[i] = (unsigned)(Rb * K + C) * 2u; }
;     const size_t kstep = (size_t)(BK * 2);
;     const size_t hstep = (size_t)HALF * K * 2;
;     const size_t tstep = 2 * hstep;
;     const size_t hstepB = Epi::PERM ? (size_t)32 * K * 2 : hstep;
;     const unsigned ldsw = (unsigned)wid * 1024u;
;     const int aoff = lds_byte(wr * 64 + fr, fq * 8), boff = lds_byte(wc * 32 + fr, fq * 8);
;     ...
;     Unit cur, nxt; int ui = 0;
;     if (!S.next(0, cur)) return;
;     f32x4 acc[2][2][4][2];
;     u32x4 iw_[Epi::HAS_INIT ? 16 : 1];
;     if constexpr (Epi::HAS_INIT) E.init_issue(iw_, cur, wr, wc, fr, fq);
;     else {
; #pragma unroll
;     for (int a = 0; a < 2; ++a)
; #pragma unroll
;         for (int b = 0; b < 2; ++b)
; #pragma unroll
;             for (int m = 0; m < 4; ++m)
; #pragma unroll
;                 for (int n = 0; n < 2; ++n) acc[a][b][m][n] = (f32x4){0.f, 0.f, 0.f, 0.f};
;     }
;     bf16x8 At[4][2], B0[2][2], B1[2][2];
;     const char* cA = (const char*)g.A + (size_t)cur.pm * tstep; const char* cB = (const char*)g.Bt + (size_t)cur.pn * tstep;
;     S.a_ready(cur);
;     if constexpr (SP2) {
;         PG8_STAGE(PG8_SB(0, 0), cB, voffB); PG8_STAGE(PG8_SB(0, 1), cB + hstepB, voffB); PG8_STAGE(PG8_SA(0, 0), cA, voffA); PG8_STAGE(PG8_SA(0, 1), cA + hstep, voffA);
;         if (wr == 1) PG8_BAR;
;         PG8_WAIT_V(2); PG8_BAR;
;         PG8_STAGE(PG8_SB(1, 0), cB + kstep, voffB); PG8_STAGE(PG8_SA(1, 0), cA + kstep, voffA); PG8_STAGE(PG8_SB(1, 1), cB + hstepB + kstep, voffB);
;         PG8_WAIT_V(6); PG8_BAR;
;     } else {
;         PG8_STAGE(PG8_SB(0, 0), cB, voffB); PG8_STAGE(PG8_SA(0, 0), cA, voffA); PG8_STAGE(PG8_SB(0, 1), cB + hstepB, voffB); PG8_STAGE(PG8_SA(0, 1), cA + hstep, voffA);
;         if (wr == 1) PG8_BAR;
.LBB0_1099:
	s_or_b64 exec, exec, s[6:7]
	v_ashrrev_i32_e32 v4, 31, v3
	v_lshrrev_b32_e32 v4, 26, v4
	v_add_u32_e32 v4, v3, v4
	v_ashrrev_i32_e32 v12, 6, v4
	v_bfe_i32 v4, v3, 27, 1
	v_lshlrev_b32_e32 v150, 4, v3
	v_lshrrev_b32_e32 v4, 22, v4
	v_add_u32_e32 v4, v150, v4
	v_and_b32_e32 v4, 0xfffffc00, v4
	v_sub_u32_e32 v4, v150, v4
	s_mov_b32 s6, s46
	s_mov_b32 s7, s35
	v_lshrrev_b32_e32 v5, 4, v4
	s_lshl_b64 s[14:15], s[6:7], 21
	v_bitop3_b32 v4, v5, v4, 32 bitop3:0x6c
	s_add_u32 s8, s0, s14
	v_ashrrev_i32_e32 v6, 31, v4
	s_addc_u32 s9, s1, s15
	v_lshrrev_b32_e32 v6, 26, v6
	s_add_u32 s12, s8, 0x100000
	v_add_u32_e32 v6, v4, v6
	s_addc_u32 s13, s9, 0
	v_lshlrev_b32_e32 v5, 3, v12
	v_ashrrev_i32_e32 v13, 6, v6
	v_and_b32_e32 v6, 0xc0, v6
	s_add_u32 s8, s0, 0xc300000
	v_and_b32_e32 v5, -16, v5
	v_sub_u32_e32 v4, v4, v6
	s_addc_u32 s9, s1, 0
	v_add_u32_e32 v133, v13, v5
	v_ashrrev_i16_sdwa v4, v205, sext(v4) dst_sel:DWORD dst_unused:UNUSED_PAD src0_sel:DWORD src1_sel:BYTE_0
	s_add_u32 s10, s0, 0x10b00000
	v_lshlrev_b32_e32 v5, 5, v12
	v_bfe_i32 v14, v4, 0, 16
	v_lshrrev_b32_e32 v4, 2, v133
	s_addc_u32 s11, s1, 0
	v_and_b32_e32 v5, 32, v5
	v_and_b32_e32 v153, 4, v4
	v_lshrrev_b32_e32 v4, 1, v3
	v_readfirstlane_b32 s18, v3
	v_add_u32_e32 v132, v5, v14
	v_lshlrev_b32_e32 v155, 1, v133
	v_and_b32_e32 v154, 3, v13
	v_and_b32_e32 v152, 15, v3
	s_cmp_gt_i32 s62, 31
	v_and_b32_e32 v151, 24, v4
	s_waitcnt vmcnt(0) lgkmcnt(0)
	s_barrier
	s_cbranch_scc1 .LBB0_1115
	v_add_u32_e32 v4, 0x2000, v150
	v_ashrrev_i32_e32 v5, 31, v4
	v_lshrrev_b32_e32 v5, 22, v5
	v_add_u32_e32 v5, v4, v5
	v_ashrrev_i32_e32 v15, 10, v5
	v_mul_i32_i24_e32 v5, 0x400, v15
	v_sub_u32_e32 v4, v4, v5
	v_lshrrev_b32_e32 v5, 4, v4
	v_bitop3_b32 v4, v5, v4, 32 bitop3:0x6c
	v_ashrrev_i32_e32 v5, 31, v4
	v_lshrrev_b32_e32 v5, 26, v5
	v_add_u32_e32 v5, v4, v5
	v_lshlrev_b32_e32 v6, 3, v15
	s_ashr_i32 s16, s62, 31
	v_ashrrev_i32_e32 v16, 6, v5
	v_and_b32_e32 v6, -16, v6
	s_lshr_b32 s16, s16, 29
	v_add_u32_e32 v6, v16, v6
	s_add_i32 s16, s62, s16
	v_lshrrev_b32_e32 v7, 2, v6
	v_lshlrev_b32_e32 v9, 1, v6
	v_and_b32_e32 v5, 0xc0, v5
	s_ashr_i32 s36, s16, 3
	s_and_b32 s16, s16, -8
	v_and_b32_e32 v7, 4, v7
	v_and_b32_e32 v8, 3, v16
	v_and_b32_e32 v9, 0x1fffd8, v9
	v_sub_u32_e32 v4, v4, v5
	s_lshl_b32 s64, s3, 3
	s_sub_i32 s16, s62, s16
	v_or3_b32 v7, v8, v7, v9
	v_lshlrev_b32_e32 v8, 5, v15
	v_ashrrev_i16_sdwa v4, v205, sext(v4) dst_sel:DWORD dst_unused:UNUSED_PAD src0_sel:DWORD src1_sel:BYTE_0
	s_add_i32 s38, s64, s16
	s_ashr_i32 s19, s18, 6
	v_and_b32_e32 v8, 32, v8
	v_bfe_i32 v17, v4, 0, 16
	s_ashr_i32 s39, s38, 31
	s_ashr_i32 s37, s36, 31
	s_ashr_i32 s20, s18, 8
	s_lshl_b32 s63, s19, 10
	v_add_lshl_u32 v4, v8, v17, 1
	s_lshl_b64 s[16:17], s[38:39], 19
	s_lshl_b64 s[22:23], s[36:37], 19
	v_lshl_add_u32 v134, v7, 11, v4
	v_lshl_add_u32 v136, v6, 11, v4
	v_and_b32_e32 v4, 0x1fffd8, v155
	s_add_u32 s42, s12, s22
	v_or3_b32 v4, v154, v4, v153
	v_lshlrev_b32_e32 v5, 1, v132
	s_addc_u32 s43, s13, s23
	s_add_i32 s37, s63, 0
	v_lshl_add_u32 v138, v4, 11, v5
	s_add_i32 m0, s37, 0x10000
	v_lshl_add_u32 v140, v133, 11, v5
	global_load_lds_dwordx4 v138, s[42:43]
	s_add_i32 m0, s37, 0x12000
	s_add_u32 s22, s42, 0x10000
	global_load_lds_dwordx4 v134, s[42:43]
	s_addc_u32 s23, s43, 0
	s_add_i32 m0, s37, 0x14000
	v_mov_b32_e32 v139, v2
	global_load_lds_dwordx4 v138, s[22:23]
	s_add_i32 m0, s37, 0x16000
	s_add_u32 s40, s8, s16
	s_addc_u32 s41, s9, s17
	s_add_i32 s39, s37, 0x2000
	global_load_lds_dwordx4 v134, s[22:23]
	s_mov_b32 m0, s37
	s_add_u32 s16, s40, 0x40000
	global_load_lds_dwordx4 v140, s[40:41]
	s_mov_b32 m0, s39
	s_addc_u32 s17, s41, 0
	s_add_i32 s65, s37, 0x4000
	global_load_lds_dwordx4 v136, s[40:41]
	s_mov_b32 m0, s65
	s_add_i32 s66, s37, 0x6000
	global_load_lds_dwordx4 v140, s[16:17]
	s_mov_b32 m0, s66
	v_mov_b32_e32 v135, v2
	global_load_lds_dwordx4 v136, s[16:17]
	v_mov_b32_e32 v141, v2
	v_mov_b32_e32 v137, v2
	s_cmp_eq_u32 s20, 1
	v_lshl_add_u64 v[10:11], s[42:43], 0, v[138:139]
	v_lshl_add_u64 v[8:9], s[42:43], 0, v[134:135]
	v_lshl_add_u64 v[4:5], s[40:41], 0, v[140:141]
	s_cselect_b64 s[16:17], -1, 0
	s_cmp_lg_u32 s20, 1
	v_lshl_add_u64 v[6:7], s[40:41], 0, v[136:137]
	s_cbranch_scc1 .LBB0_1102
	s_nop 0
.LBB0_1102:
	v_lshlrev_b32_e32 v18, 1, v151
	v_lshlrev_b32_e32 v19, 2, v152
	s_and_b32 s21, s19, 3
	v_lshl_or_b32 v18, v152, 6, v18
	s_lshl_b32 s19, s20, 13
	v_and_b32_e32 v20, 32, v19
	s_add_i32 m0, s37, 0x18000
	v_lshl_add_u64 v[10:11], v[10:11], 0, s[52:53]
	v_bitop3_b32 v21, v18, s19, v20 bitop3:0xde
	s_lshl_b32 s19, s21, 12
	s_nop 0
	s_nop 0
	global_load_lds_dwordx4 v[10:11], off
	v_lshl_add_u64 v[8:9], v[8:9], 0, s[52:53]
	s_add_i32 m0, s37, 0x1a000
	s_add_i32 s67, s37, 0x8000
	s_add_i32 s76, s37, 0xa000
	global_load_lds_dwordx4 v[8:9], off
	v_lshl_add_u64 v[4:5], v[4:5], 0, s[52:53]
	s_mov_b32 m0, s67
	s_add_u32 s22, s42, 0x10080
	global_load_lds_dwordx4 v[4:5], off
	v_lshl_add_u64 v[4:5], v[6:7], 0, s[52:53]
	s_mov_b32 m0, s76
	s_addc_u32 s23, s43, 0
	global_load_lds_dwordx4 v[4:5], off
	s_add_i32 m0, s37, 0x1c000
	v_lshl_add_u64 v[4:5], s[22:23], 0, v[138:139]
	global_load_lds_dwordx4 v[4:5], off
	v_lshl_add_u64 v[4:5], s[22:23], 0, v[134:135]
	s_add_i32 m0, s37, 0x1e000
	s_cmpk_lt_u32 s18, 0x100
	global_load_lds_dwordx4 v[4:5], off
	v_cmp_lt_u32_e32 vcc, 7, v152
	v_bitop3_b32 v157, s19, v18, v20 bitop3:0xf6
	s_cselect_b64 s[18:19], -1, 0
	s_lshl_b32 s21, s21, 6
	v_cndmask_b32_e64 v4, 0, 32, vcc
	v_or3_b32 v161, s21, v4, v151
	v_lshlrev_b32_e32 v4, 14, v12
	v_and_b32_e32 v4, 0xffff8000, v4
	v_lshl_add_u32 v4, v13, 11, v4
	v_and_b32_e32 v5, 1, v12
	v_lshl_or_b32 v4, v5, 6, v4
	v_lshl_add_u32 v142, v14, 1, v4
	v_lshlrev_b32_e32 v4, 14, v15
	v_lshl_or_b32 v156, s20, 6, v152
	s_lshl_b32 s20, s20, 8
	v_and_b32_e32 v4, 0xffff8000, v4
	s_cmp_lg_u32 s16, 0
	s_cbranch_scc0 .Lpd3
	s_barrier
.Lpd3:
	s_waitcnt vmcnt(8)
	s_barrier
	s_waitcnt vmcnt(6)
	s_add_i32 s20, s20, 0
	v_lshl_add_u32 v4, v16, 11, v4
	v_and_b32_e32 v5, 1, v15
	s_add_i32 s20, s20, 0x20000
	v_lshl_or_b32 v4, v5, 6, v4
	s_mov_b32 s78, 0
	v_cndmask_b32_e64 v158, 0, -8, vcc
	v_cndmask_b32_e64 v159, 8, 0, vcc
	v_add_u32_e32 v160, s20, v19
	v_mov_b32_e32 v143, v2
	v_lshl_add_u32 v144, v17, 1, v4
	v_mov_b32_e32 v145, v2
	v_add_u32_e32 v162, 0, v21
	s_barrier
	s_branch .LBB0_1105

; #define PG8_WAIT_V(n) asm volatile("s_waitcnt vmcnt(" #n ")" ::: "memory")
; #define PG8_BAR __builtin_amdgcn_s_barrier()
;     DI void init_issue(u32x4 (&w)[R8::HAS_PRE ? 16 : 1], const Unit& u, int wr, int wc, int fr, int fq) const {
;     ...
;             const int row0 = u.pm * BM + wr * 64 + fr, col0 = u.pn * BM + (PERM ? wc * 64 : wc * 32) + 8 * fq;
; #pragma unroll
;             for (int ai = 0; ai < 2; ++ai)
; #pragma unroll
;                 for (int m = 0; m < 4; ++m)
; #pragma unroll
;                     for (int bj = 0; bj < 2; ++bj) w[(ai * 4 + m) * 2 + bj] = e.pre(row0 + ai * HALF + m * 16, col0 + bj * (PERM ? 32 : HALF));
; template <class Epi, class Sched, bool ALIGN_EPI = false, bool SP2 = false>
; __device__ __forceinline__ void gemm_phase(PG8_LAS unsigned char* lds, const Gemm g, const Sched& S, const Epi& E, const int tid) {
;     ...
;     for (int i = 0; i < 2; ++i) { int R, C; stage_rc(tid * 16 + i * 8192, R, C); const int Rb = Epi::PERM ? (2 * (R & ~31) + perm32(R & 31)) : R;
;         voffA[i] = (unsigned)(R * K + C) * 2u; voffB[i] = (unsigned)(Rb * K + C) * 2u; }
;     const size_t kstep = (size_t)(BK * 2);
;     const size_t hstep = (size_t)HALF * K * 2;
;     const size_t tstep = 2 * hstep;
;     const size_t hstepB = Epi::PERM ? (size_t)32 * K * 2 : hstep;
;     const unsigned ldsw = (unsigned)wid * 1024u;
;     const int aoff = lds_byte(wr * 64 + fr, fq * 8), boff = lds_byte(wc * 32 + fr, fq * 8);
;     ...
;     Unit cur, nxt; int ui = 0;
;     if (!S.next(0, cur)) return;
;     f32x4 acc[2][2][4][2];
;     u32x4 iw_[Epi::HAS_INIT ? 16 : 1];
;     if constexpr (Epi::HAS_INIT) E.init_issue(iw_, cur, wr, wc, fr, fq);
;     else {
; #pragma unroll
;     for (int a = 0; a < 2; ++a)
; #pragma unroll
;         for (int b = 0; b < 2; ++b)
; #pragma unroll
;             for (int m = 0; m < 4; ++m)
; #pragma unroll
;                 for (int n = 0; n < 2; ++n) acc[a][b][m][n] = (f32x4){0.f, 0.f, 0.f, 0.f};
;     }
;     bf16x8 At[4][2], B0[2][2], B1[2][2];
;     const char* cA = (const char*)g.A + (size_t)cur.pm * tstep; const char* cB = (const char*)g.Bt + (size_t)cur.pn * tstep;
;     S.a_ready(cur);
;     if constexpr (SP2) {
;         PG8_STAGE(PG8_SB(0, 0), cB, voffB); PG8_STAGE(PG8_SB(0, 1), cB + hstepB, voffB); PG8_STAGE(PG8_SA(0, 0), cA, voffA); PG8_STAGE(PG8_SA(0, 1), cA + hstep, voffA);
;         if (wr == 1) PG8_BAR;
;         PG8_WAIT_V(2); PG8_BAR;
.LBB0_1257:
	v_ashrrev_i32_e32 v5, 31, v3
	v_lshrrev_b32_e32 v5, 26, v5
	v_add_u32_e32 v5, v3, v5
	v_ashrrev_i32_e32 v142, 6, v5
	v_bfe_i32 v5, v3, 27, 1
	v_lshlrev_b32_e32 v4, 4, v3
	v_lshrrev_b32_e32 v5, 22, v5
	v_add_u32_e32 v5, v4, v5
	v_and_b32_e32 v5, 0xfffffc00, v5
	s_ashr_i32 s54, s16, 6
	s_lshl_b64 s[8:9], s[8:9], 1
	v_sub_u32_e32 v5, v4, v5
	s_waitcnt lgkmcnt(0)
	s_add_u32 s8, s0, s8
	v_lshrrev_b32_e32 v6, 4, v5
	s_addc_u32 s9, s1, s9
	v_bitop3_b32 v5, v6, v5, 32 bitop3:0x6c
	s_add_u32 s12, s8, 0x900000
	v_ashrrev_i32_e32 v7, 31, v5
	s_addc_u32 s13, s9, 0
	v_lshrrev_b32_e32 v7, 26, v7
	s_add_u32 s8, s0, 0x12d00000
	v_add_u32_e32 v7, v5, v7
	s_addc_u32 s9, s1, 0
	v_lshlrev_b32_e32 v6, 3, v142
	v_ashrrev_i32_e32 v143, 6, v7
	v_and_b32_e32 v7, 0xc0, v7
	s_add_u32 s10, s0, 0xc300000
	v_and_b32_e32 v6, -16, v6
	v_sub_u32_e32 v5, v5, v7
	s_addc_u32 s11, s1, 0
	v_add_u32_e32 v133, v143, v6
	v_lshlrev_b32_e32 v6, 5, v142
	v_ashrrev_i16_sdwa v5, v205, sext(v5) dst_sel:DWORD dst_unused:UNUSED_PAD src0_sel:DWORD src1_sel:BYTE_0
	s_add_u32 s0, s0, 0x2e200000
	v_and_b32_e32 v6, 32, v6
	v_bfe_i32 v144, v5, 0, 16
	v_lshrrev_b32_e32 v5, 2, v133
	s_addc_u32 s1, s1, 0
	v_add_u32_e32 v132, v6, v144
	v_lshlrev_b32_e32 v155, 1, v133
	v_and_b32_e32 v153, 4, v5
	v_and_b32_e32 v154, 3, v143
	v_and_b32_e32 v152, 15, v3
	s_andn2_b64 vcc, exec, s[4:5]
	s_lshl_b32 s55, s54, 10
	s_cbranch_vccnz .LBB0_1305
	v_and_b32_e32 v5, 0x1fffd8, v155
	v_or3_b32 v5, v154, v5, v153
	v_lshlrev_b32_e32 v6, 1, v132
	v_add_u32_e32 v4, 0x2000, v4
	v_lshl_add_u32 v136, v5, 11, v6
	v_ashrrev_i32_e32 v5, 31, v4
	v_lshrrev_b32_e32 v5, 22, v5
	v_add_u32_e32 v5, v4, v5
	v_ashrrev_i32_e32 v145, 10, v5
	v_mul_i32_i24_e32 v5, 0x400, v145
	v_sub_u32_e32 v4, v4, v5
	v_lshrrev_b32_e32 v5, 4, v4
	v_bitop3_b32 v4, v5, v4, 32 bitop3:0x6c
	v_lshl_add_u32 v134, v133, 11, v6
	v_ashrrev_i32_e32 v6, 31, v4
	v_lshrrev_b32_e32 v6, 26, v6
	v_add_u32_e32 v6, v4, v6
	v_lshlrev_b32_e32 v5, 3, v145
	v_ashrrev_i32_e32 v147, 6, v6
	v_and_b32_e32 v6, 0xc0, v6
	v_and_b32_e32 v5, -16, v5
	v_sub_u32_e32 v4, v4, v6
	v_add_u32_e32 v5, v147, v5
	v_ashrrev_i16_sdwa v4, v205, sext(v4) dst_sel:DWORD dst_unused:UNUSED_PAD src0_sel:DWORD src1_sel:BYTE_0
	v_lshlrev_b32_e32 v7, 5, v145
	v_bfe_i32 v148, v4, 0, 16
	v_lshlrev_b32_e32 v4, 1, v5
	v_lshrrev_b32_e32 v6, 2, v5
	s_ashr_i32 s5, s16, 8
	v_and_b32_e32 v7, 32, v7
	v_and_b32_e32 v6, 4, v6
	v_and_b32_e32 v8, 3, v147
	v_and_b32_e32 v4, 0x1fffd8, v4
	s_lshl_b32 s17, s5, 6
	s_lshl_b32 s14, s30, 8
	s_and_b32 s4, s54, 3
	v_or3_b32 v4, v8, v6, v4
	v_add_lshl_u32 v6, v7, v148, 1
	s_add_i32 s14, s14, s17
	v_bfe_u32 v146, v3, 4, 2
	v_lshl_add_u32 v140, v4, 11, v6
	v_or_b32_e32 v4, s14, v152
	s_lshl_b32 s14, s28, 8
	s_lshl_b32 s62, s4, 6
	v_lshlrev_b32_e32 v156, 3, v146
	s_or_b32 s14, s14, s62
	v_or_b32_e32 v10, 16, v4
	v_lshl_add_u32 v138, v5, 11, v6
	v_or_b32_e32 v6, s14, v156
	v_ashrrev_i32_e32 v5, 31, v4
	v_ashrrev_i32_e32 v11, 31, v10
	v_lshlrev_b64 v[8:9], 11, v[4:5]
	v_ashrrev_i32_e32 v7, 31, v6
	v_lshlrev_b64 v[10:11], 11, v[10:11]
	v_lshl_add_u64 v[8:9], s[10:11], 0, v[8:9]
	v_lshlrev_b64 v[6:7], 1, v[6:7]
	v_lshl_add_u64 v[10:11], s[10:11], 0, v[10:11]
	v_lshl_add_u64 v[8:9], v[8:9], 0, v[6:7]
	v_lshl_add_u64 v[10:11], v[10:11], 0, v[6:7]
	global_load_dwordx4 v[64:67], v[8:9], off
	global_load_dwordx4 v[56:59], v[8:9], off offset:64
	global_load_dwordx4 v[60:63], v[10:11], off
	global_load_dwordx4 v[48:51], v[10:11], off offset:64
	v_or_b32_e32 v10, 32, v4
	v_or_b32_e32 v4, 48, v4
	v_ashrrev_i32_e32 v11, 31, v10
	v_ashrrev_i32_e32 v5, 31, v4
	v_lshlrev_b64 v[10:11], 11, v[10:11]
	v_lshlrev_b64 v[4:5], 11, v[4:5]
	v_lshl_add_u64 v[10:11], s[10:11], 0, v[10:11]
	v_lshl_add_u64 v[4:5], s[10:11], 0, v[4:5]
	v_lshl_add_u64 v[10:11], v[10:11], 0, v[6:7]
	v_lshl_add_u64 v[4:5], v[4:5], 0, v[6:7]
	v_add_co_u32_e32 v6, vcc, s57, v8
	global_load_dwordx4 v[52:55], v[10:11], off
	global_load_dwordx4 v[40:43], v[10:11], off offset:64
	v_addc_co_u32_e32 v7, vcc, 0, v9, vcc
	global_load_dwordx4 v[44:47], v[4:5], off
	global_load_dwordx4 v[36:39], v[4:5], off offset:64
	v_lshl_add_u64 v[4:5], v[8:9], 0, s[50:51]
	global_load_dwordx4 v[32:35], v[6:7], off
	global_load_dwordx4 v[28:31], v[4:5], off offset:64
	v_add_co_u32_e32 v6, vcc, s26, v8
	s_mov_b32 s14, 0x50000
	s_nop 0
	v_addc_co_u32_e32 v7, vcc, 0, v9, vcc
	v_lshl_add_u64 v[4:5], v[8:9], 0, s[72:73]
	global_load_dwordx4 v[24:27], v[6:7], off
	global_load_dwordx4 v[20:23], v[4:5], off offset:64
	v_add_co_u32_e32 v6, vcc, s14, v8
	s_mov_b64 s[14:15], 0x58000
	s_nop 0
	v_addc_co_u32_e32 v7, vcc, 0, v9, vcc
	v_lshl_add_u64 v[16:17], v[8:9], 0, s[14:15]
	s_mov_b32 s14, 0x58000
	s_ashr_i32 s31, s30, 31
	s_ashr_i32 s29, s28, 31
	v_lshl_add_u64 v[4:5], v[8:9], 0, s[74:75]
	v_add_co_u32_e32 v8, vcc, s14, v8
	s_lshl_b64 s[14:15], s[30:31], 19
	s_lshl_b64 s[18:19], s[28:29], 19
	s_add_u32 s38, s12, s18
	s_addc_u32 s39, s13, s19
	s_add_i32 s31, s55, 0
	v_addc_co_u32_e32 v9, vcc, 0, v9, vcc
	s_add_i32 m0, s31, 0x10000
	global_load_dwordx4 v[12:15], v[6:7], off
	s_nop 0
	global_load_dwordx4 v[4:7], v[4:5], off offset:64
	s_nop 0
	global_load_dwordx4 v[8:11], v[8:9], off
	s_nop 0
	global_load_dwordx4 v[16:19], v[16:17], off offset:64
	v_mov_b32_e32 v137, v2
	global_load_lds_dwordx4 v136, s[38:39]
	s_add_i32 m0, s31, 0x12000
	s_add_u32 s18, s38, 0x10000
	global_load_lds_dwordx4 v140, s[38:39]
	s_addc_u32 s19, s39, 0
	s_add_i32 m0, s31, 0x14000
	v_mov_b32_e32 v141, v2
	global_load_lds_dwordx4 v136, s[18:19]
	s_add_i32 m0, s31, 0x16000
	s_add_u32 s40, s8, s14
	s_addc_u32 s41, s9, s15
	s_add_i32 s63, s31, 0x2000
	global_load_lds_dwordx4 v140, s[18:19]
	s_mov_b32 m0, s31
	s_add_u32 s14, s40, 0x40000
	global_load_lds_dwordx4 v134, s[40:41]
	s_mov_b32 m0, s63
	s_addc_u32 s15, s41, 0
	s_add_i32 s64, s31, 0x4000
	global_load_lds_dwordx4 v138, s[40:41]
	s_mov_b32 m0, s64
	s_add_i32 s65, s31, 0x6000
	global_load_lds_dwordx4 v134, s[14:15]
	s_mov_b32 m0, s65
	v_mov_b32_e32 v135, v2
	global_load_lds_dwordx4 v138, s[14:15]
	v_mov_b32_e32 v139, v2
	s_cmp_eq_u32 s5, 1
	v_lshl_add_u64 v[74:75], s[38:39], 0, v[136:137]
	v_lshl_add_u64 v[72:73], s[38:39], 0, v[140:141]
	v_lshl_add_u64 v[68:69], s[40:41], 0, v[134:135]
	s_cselect_b64 s[14:15], -1, 0
	s_cmp_lg_u32 s5, 1
	v_lshl_add_u64 v[70:71], s[40:41], 0, v[138:139]
	s_cbranch_scc1 .LBB0_1260
	s_nop 0
; DI float bf_lo(unsigned u) { return __uint_as_float(u << 16); }
; DI float bf_hi(unsigned u) { return __uint_as_float(u & 0xffff0000u); }
; #define PG8_STAGE(bufoff, gbase, voff) do { _Pragma("unroll") for (int _i = 0; _i < 2; ++_i) \
;         __builtin_amdgcn_global_load_lds((const unsigned*)((const char*)(gbase) + (voff)[_i]), (PG8_LAS unsigned*)(lds + (bufoff) + ldsw + _i * 8192), 16, 0, 0); } while (0)
; #define PG8_WAIT_V(n) asm volatile("s_waitcnt vmcnt(" #n ")" ::: "memory")
; #define PG8_BAR __builtin_amdgcn_s_barrier()
;     DI void init_finish(f32x4 (&acc)[2][2][4][2], const u32x4 (&w)[R8::HAS_PRE ? 16 : 1]) const {
;     ...
; #pragma unroll
;             for (int ai = 0; ai < 2; ++ai)
; #pragma unroll
;                 for (int m = 0; m < 4; ++m)
; #pragma unroll
;                     for (int bj = 0; bj < 2; ++bj) { const u32x4 v = w[(ai * 4 + m) * 2 + bj];
;                         acc[ai][bj][m][0] = (f32x4){bf_lo(v.x), bf_hi(v.x), bf_lo(v.y), bf_hi(v.y)}; acc[ai][bj][m][1] = (f32x4){bf_lo(v.z), bf_hi(v.z), bf_lo(v.w), bf_hi(v.w)}; }
; template <class Epi, class Sched, bool ALIGN_EPI = false, bool SP2 = false>
; __device__ __forceinline__ void gemm_phase(PG8_LAS unsigned char* lds, const Gemm g, const Sched& S, const Epi& E, const int tid) {
;     ...
;         if (wr == 1) PG8_BAR;
;         PG8_WAIT_V(2); PG8_BAR;
;         PG8_STAGE(PG8_SB(1, 0), cB + kstep, voffB); PG8_STAGE(PG8_SA(1, 0), cA + kstep, voffA); PG8_STAGE(PG8_SB(1, 1), cB + hstepB + kstep, voffB);
;         PG8_WAIT_V(6); PG8_BAR;
;     } else {
;         PG8_STAGE(PG8_SB(0, 0), cB, voffB); PG8_STAGE(PG8_SA(0, 0), cA, voffA); PG8_STAGE(PG8_SB(0, 1), cB + hstepB, voffB); PG8_STAGE(PG8_SA(0, 1), cA + hstep, voffA);
;         if (wr == 1) PG8_BAR;
;         PG8_WAIT_V(4); PG8_BAR;
;         PG8_STAGE(PG8_SB(1, 0), cB + kstep, voffB); PG8_STAGE(PG8_SA(1, 0), cA + kstep, voffA); PG8_STAGE(PG8_SB(1, 1), cB + hstepB + kstep, voffB);
;         PG8_WAIT_V(6); PG8_BAR;
;     }
;     if constexpr (Epi::HAS_INIT) E.init_finish(acc, iw_);
.LBB0_1260:
	v_or_b32_e32 v157, s17, v152
	v_lshlrev_b32_e32 v76, 6, v157
	v_lshlrev_b32_e32 v77, 4, v146
	s_movk_i32 s17, 0x3c0
	v_lshlrev_b32_e32 v78, 2, v157
	v_and_or_b32 v76, v76, s17, v77
	s_lshl_b32 s5, s5, 13
	v_and_b32_e32 v78, 32, v78
	v_bitop3_b32 v149, v76, s5, v78 bitop3:0xde
	v_lshl_or_b32 v76, v152, 6, v77
	v_lshlrev_b32_e32 v77, 2, v152
	s_add_i32 m0, s31, 0x18000
	v_lshl_add_u64 v[74:75], v[74:75], 0, s[52:53]
	s_lshl_b32 s4, s4, 12
	v_and_b32_e32 v77, 32, v77
	s_nop 0
	s_nop 0
	global_load_lds_dwordx4 v[74:75], off
	v_lshl_add_u64 v[72:73], v[72:73], 0, s[52:53]
	s_add_i32 m0, s31, 0x1a000
	s_add_i32 s66, s31, 0x8000
	s_add_i32 s67, s31, 0xa000
	v_bitop3_b32 v158, v76, s4, v77 bitop3:0xde
	global_load_lds_dwordx4 v[72:73], off
	v_lshl_add_u64 v[68:69], v[68:69], 0, s[52:53]
	s_mov_b32 m0, s66
	s_add_u32 s4, s38, 0x10080
	global_load_lds_dwordx4 v[68:69], off
	v_lshl_add_u64 v[68:69], v[70:71], 0, s[52:53]
	s_mov_b32 m0, s67
	s_addc_u32 s5, s39, 0
	global_load_lds_dwordx4 v[68:69], off
	s_add_i32 m0, s31, 0x1c000
	v_lshl_add_u64 v[68:69], s[4:5], 0, v[136:137]
	global_load_lds_dwordx4 v[68:69], off
	v_lshl_add_u64 v[68:69], s[4:5], 0, v[140:141]
	s_add_i32 m0, s31, 0x1e000
	v_cmp_eq_u32_e64 s[4:5], 0, v146
	global_load_lds_dwordx4 v[68:69], off
	v_lshlrev_b32_e32 v146, 14, v142
	v_and_b32_e32 v146, 0xffff8000, v146
	v_lshl_add_u32 v143, v143, 11, v146
	v_and_b32_e32 v142, 1, v142
	v_lshl_or_b32 v142, v142, 6, v143
	v_lshl_add_u32 v142, v144, 1, v142
	v_lshlrev_b32_e32 v144, 14, v145
	v_and_b32_e32 v144, 0xffff8000, v144
	s_cmp_lg_u32 s14, 0
	s_cbranch_scc0 .Lpd4
	s_barrier
.Lpd4:
	s_waitcnt vmcnt(8)
	s_barrier
	s_waitcnt vmcnt(6)
	v_lshl_add_u32 v144, v147, 11, v144
	v_and_b32_e32 v145, 1, v145
	s_cmpk_lt_u32 s16, 0x100
	v_lshl_or_b32 v144, v145, 6, v144
	s_waitcnt vmcnt(0)
	v_lshlrev_b32_e32 v120, 16, v64
	v_and_b32_e32 v121, 0xffff0000, v64
	v_lshlrev_b32_e32 v122, 16, v65
	v_and_b32_e32 v123, 0xffff0000, v65
	v_lshlrev_b32_e32 v128, 16, v66
	v_and_b32_e32 v129, 0xffff0000, v66
	v_lshlrev_b32_e32 v130, 16, v67
	v_and_b32_e32 v131, 0xffff0000, v67
	v_lshlrev_b32_e32 v116, 16, v56
	v_and_b32_e32 v117, 0xffff0000, v56
	v_lshlrev_b32_e32 v118, 16, v57
	v_and_b32_e32 v119, 0xffff0000, v57
	v_lshlrev_b32_e32 v124, 16, v58
	v_and_b32_e32 v125, 0xffff0000, v58
	v_lshlrev_b32_e32 v126, 16, v59
	v_and_b32_e32 v127, 0xffff0000, v59
	v_lshlrev_b32_e32 v100, 16, v60
	v_and_b32_e32 v101, 0xffff0000, v60
	v_lshlrev_b32_e32 v102, 16, v61
	v_and_b32_e32 v103, 0xffff0000, v61
	v_lshlrev_b32_e32 v108, 16, v62
	v_and_b32_e32 v109, 0xffff0000, v62
	v_lshlrev_b32_e32 v110, 16, v63
	v_and_b32_e32 v111, 0xffff0000, v63
	v_lshlrev_b32_e32 v104, 16, v48
	v_and_b32_e32 v105, 0xffff0000, v48
	v_lshlrev_b32_e32 v106, 16, v49
	v_and_b32_e32 v107, 0xffff0000, v49
	v_lshlrev_b32_e32 v112, 16, v50
	v_and_b32_e32 v113, 0xffff0000, v50
	v_lshlrev_b32_e32 v114, 16, v51
	v_and_b32_e32 v115, 0xffff0000, v51
	v_lshlrev_b32_e32 v84, 16, v52
	v_and_b32_e32 v85, 0xffff0000, v52
	v_lshlrev_b32_e32 v86, 16, v53
	v_and_b32_e32 v87, 0xffff0000, v53
	v_lshlrev_b32_e32 v92, 16, v54
	v_and_b32_e32 v93, 0xffff0000, v54
	v_lshlrev_b32_e32 v94, 16, v55
	v_and_b32_e32 v95, 0xffff0000, v55
	v_lshlrev_b32_e32 v88, 16, v40
	v_and_b32_e32 v89, 0xffff0000, v40
	v_lshlrev_b32_e32 v90, 16, v41
	v_and_b32_e32 v91, 0xffff0000, v41
	v_lshlrev_b32_e32 v96, 16, v42
	v_and_b32_e32 v97, 0xffff0000, v42
	v_lshlrev_b32_e32 v98, 16, v43
	v_and_b32_e32 v99, 0xffff0000, v43
	v_lshlrev_b32_e32 v68, 16, v44
	v_and_b32_e32 v69, 0xffff0000, v44
	v_lshlrev_b32_e32 v70, 16, v45
	v_and_b32_e32 v71, 0xffff0000, v45
	v_lshlrev_b32_e32 v76, 16, v46
	v_and_b32_e32 v77, 0xffff0000, v46
	v_lshlrev_b32_e32 v78, 16, v47
	v_and_b32_e32 v79, 0xffff0000, v47
	v_lshlrev_b32_e32 v72, 16, v36
	v_and_b32_e32 v73, 0xffff0000, v36
	v_lshlrev_b32_e32 v74, 16, v37
	v_and_b32_e32 v75, 0xffff0000, v37
	v_lshlrev_b32_e32 v80, 16, v38
	v_and_b32_e32 v81, 0xffff0000, v38
	v_lshlrev_b32_e32 v82, 16, v39
	v_and_b32_e32 v83, 0xffff0000, v39
	v_lshlrev_b32_e32 v52, 16, v32
	v_and_b32_e32 v53, 0xffff0000, v32
	v_lshlrev_b32_e32 v54, 16, v33
	v_and_b32_e32 v55, 0xffff0000, v33
	v_lshlrev_b32_e32 v60, 16, v34
	v_and_b32_e32 v61, 0xffff0000, v34
	v_lshlrev_b32_e32 v62, 16, v35
	v_and_b32_e32 v63, 0xffff0000, v35
	v_lshlrev_b32_e32 v56, 16, v28
	v_and_b32_e32 v57, 0xffff0000, v28
	v_lshlrev_b32_e32 v58, 16, v29
	v_and_b32_e32 v59, 0xffff0000, v29
	v_lshlrev_b32_e32 v64, 16, v30
	v_and_b32_e32 v65, 0xffff0000, v30
	v_lshlrev_b32_e32 v66, 16, v31
	v_and_b32_e32 v67, 0xffff0000, v31
	v_lshlrev_b32_e32 v36, 16, v24
	v_and_b32_e32 v37, 0xffff0000, v24
	v_lshlrev_b32_e32 v38, 16, v25
	v_and_b32_e32 v39, 0xffff0000, v25
	v_lshlrev_b32_e32 v44, 16, v26
	v_and_b32_e32 v45, 0xffff0000, v26
	v_lshlrev_b32_e32 v46, 16, v27
	v_and_b32_e32 v47, 0xffff0000, v27
	v_lshlrev_b32_e32 v40, 16, v20
	v_and_b32_e32 v41, 0xffff0000, v20
	v_lshlrev_b32_e32 v42, 16, v21
	v_and_b32_e32 v43, 0xffff0000, v21
	v_lshlrev_b32_e32 v48, 16, v22
	v_and_b32_e32 v49, 0xffff0000, v22
	v_lshlrev_b32_e32 v50, 16, v23
	v_and_b32_e32 v51, 0xffff0000, v23
	v_lshlrev_b32_e32 v20, 16, v12
	v_and_b32_e32 v21, 0xffff0000, v12
	v_lshlrev_b32_e32 v22, 16, v13
	v_and_b32_e32 v23, 0xffff0000, v13
	v_lshlrev_b32_e32 v28, 16, v14
	v_and_b32_e32 v29, 0xffff0000, v14
	v_lshlrev_b32_e32 v30, 16, v15
	v_and_b32_e32 v31, 0xffff0000, v15
	v_lshlrev_b32_e32 v24, 16, v4
	v_and_b32_e32 v25, 0xffff0000, v4
	v_lshlrev_b32_e32 v26, 16, v5
	v_and_b32_e32 v27, 0xffff0000, v5
	v_lshlrev_b32_e32 v32, 16, v6
	v_and_b32_e32 v33, 0xffff0000, v6
	v_lshlrev_b32_e32 v34, 16, v7
	v_and_b32_e32 v35, 0xffff0000, v7
	v_lshlrev_b32_e32 v4, 16, v8
	v_and_b32_e32 v5, 0xffff0000, v8
	v_lshlrev_b32_e32 v6, 16, v9
	v_and_b32_e32 v7, 0xffff0000, v9
	v_lshlrev_b32_e32 v12, 16, v10
	v_and_b32_e32 v13, 0xffff0000, v10
	v_lshlrev_b32_e32 v14, 16, v11
	v_and_b32_e32 v15, 0xffff0000, v11
	v_lshlrev_b32_e32 v8, 16, v16
	v_and_b32_e32 v9, 0xffff0000, v16
	v_lshlrev_b32_e32 v10, 16, v17
	v_and_b32_e32 v11, 0xffff0000, v17
	v_lshlrev_b32_e32 v16, 16, v18
	v_and_b32_e32 v17, 0xffff0000, v18
	v_lshlrev_b32_e32 v18, 16, v19
	v_and_b32_e32 v19, 0xffff0000, v19
	s_cselect_b64 s[16:17], -1, 0
	s_mov_b32 s76, 0
	s_lshl_b32 s78, s27, 3
	v_or_b32_e32 v159, s62, v156
	v_mov_b32_e32 v143, v2
	v_lshl_add_u32 v144, v148, 1, v144
	v_mov_b32_e32 v145, v2
	v_add_u32_e32 v160, 0, v149
	s_barrier
	s_branch .LBB0_1263

; template <class Epi, class Sched, bool ALIGN_EPI = false, bool SP2 = false>
; __device__ __forceinline__ void gemm_phase(PG8_LAS unsigned char* lds, const Gemm g, const Sched& S, const Epi& E, const int tid) {
;     ...
;     for (int i = 0; i < 2; ++i) { int R, C; stage_rc(tid * 16 + i * 8192, R, C); const int Rb = Epi::PERM ? (2 * (R & ~31) + perm32(R & 31)) : R;
;         voffA[i] = (unsigned)(R * K + C) * 2u; voffB[i] = (unsigned)(Rb * K + C) * 2u; }
;     const size_t kstep = (size_t)(BK * 2);
;     const size_t hstep = (size_t)HALF * K * 2;
;     const size_t tstep = 2 * hstep;
;     const size_t hstepB = Epi::PERM ? (size_t)32 * K * 2 : hstep;
;     const unsigned ldsw = (unsigned)wid * 1024u;
;     const int aoff = lds_byte(wr * 64 + fr, fq * 8), boff = lds_byte(wc * 32 + fr, fq * 8);
;     ...
;     Unit cur, nxt; int ui = 0;
;     if (!S.next(0, cur)) return;
;     f32x4 acc[2][2][4][2];
;     u32x4 iw_[Epi::HAS_INIT ? 16 : 1];
;     if constexpr (Epi::HAS_INIT) E.init_issue(iw_, cur, wr, wc, fr, fq);
;     else {
; #pragma unroll
;     for (int a = 0; a < 2; ++a)
; #pragma unroll
;         for (int b = 0; b < 2; ++b)
; #pragma unroll
;             for (int m = 0; m < 4; ++m)
; #pragma unroll
;                 for (int n = 0; n < 2; ++n) acc[a][b][m][n] = (f32x4){0.f, 0.f, 0.f, 0.f};
;     }
;     bf16x8 At[4][2], B0[2][2], B1[2][2];
;     const char* cA = (const char*)g.A + (size_t)cur.pm * tstep; const char* cB = (const char*)g.Bt + (size_t)cur.pn * tstep;
;     S.a_ready(cur);
;     if constexpr (SP2) {
;         PG8_STAGE(PG8_SB(0, 0), cB, voffB); PG8_STAGE(PG8_SB(0, 1), cB + hstepB, voffB); PG8_STAGE(PG8_SA(0, 0), cA, voffA); PG8_STAGE(PG8_SA(0, 1), cA + hstep, voffA);
;         if (wr == 1) PG8_BAR;
;         PG8_WAIT_V(2); PG8_BAR;
;         PG8_STAGE(PG8_SB(1, 0), cB + kstep, voffB); PG8_STAGE(PG8_SA(1, 0), cA + kstep, voffA); PG8_STAGE(PG8_SB(1, 1), cB + hstepB + kstep, voffB);
;         PG8_WAIT_V(6); PG8_BAR;
;     } else {
;         PG8_STAGE(PG8_SB(0, 0), cB, voffB); PG8_STAGE(PG8_SA(0, 0), cA, voffA); PG8_STAGE(PG8_SB(0, 1), cB + hstepB, voffB); PG8_STAGE(PG8_SA(0, 1), cA + hstep, voffA);
;         if (wr == 1) PG8_BAR;
;         PG8_WAIT_V(4); PG8_BAR;
;         PG8_STAGE(PG8_SB(1, 0), cB + kstep, voffB); PG8_STAGE(PG8_SA(1, 0), cA + kstep, voffA); PG8_STAGE(PG8_SB(1, 1), cB + hstepB + kstep, voffB);
;         PG8_WAIT_V(6); PG8_BAR;
.LBB0_1371:
	s_or_b64 exec, exec, s[0:1]
	v_ashrrev_i32_e32 v3, 31, v152
	v_lshrrev_b32_e32 v3, 26, v3
	v_add_u32_e32 v3, v152, v3
	v_ashrrev_i32_e32 v12, 6, v3
	v_bfe_i32 v3, v152, 27, 1
	v_lshlrev_b32_e32 v4, 4, v152
	v_lshrrev_b32_e32 v3, 22, v3
	v_add_u32_e32 v3, v4, v3
	v_and_b32_e32 v3, 0xfffffc00, v3
	v_sub_u32_e32 v3, v4, v3
	v_lshrrev_b32_e32 v5, 4, v3
	s_lshl_b64 s[0:1], s[6:7], 23
	v_bitop3_b32 v3, v5, v3, 32 bitop3:0x6c
	s_add_u32 s6, s4, s0
	v_ashrrev_i32_e32 v6, 31, v3
	s_addc_u32 s7, s5, s1
	v_lshrrev_b32_e32 v6, 26, v6
	s_add_u32 s10, s6, 0x2100000
	v_add_u32_e32 v6, v3, v6
	s_addc_u32 s11, s7, 0
	v_lshlrev_b32_e32 v5, 3, v12
	v_ashrrev_i32_e32 v13, 6, v6
	v_and_b32_e32 v6, 0xc0, v6
	s_add_u32 s6, s4, 0xc300000
	v_and_b32_e32 v5, -16, v5
	v_sub_u32_e32 v3, v3, v6
	s_addc_u32 s7, s5, 0
	v_add_u32_e32 v133, v13, v5
	v_ashrrev_i16_sdwa v3, v205, sext(v3) dst_sel:DWORD dst_unused:UNUSED_PAD src0_sel:DWORD src1_sel:BYTE_0
	s_add_u32 s4, s4, 0x17100000
	v_lshlrev_b32_e32 v5, 5, v12
	v_bfe_i32 v14, v3, 0, 16
	v_lshrrev_b32_e32 v3, 2, v133
	s_addc_u32 s5, s5, 0
	v_and_b32_e32 v5, 32, v5
	v_and_b32_e32 v154, 4, v3
	v_lshrrev_b32_e32 v3, 1, v152
	v_readfirstlane_b32 s14, v152
	v_add_u32_e32 v132, v5, v14
	v_lshlrev_b32_e32 v156, 1, v133
	v_and_b32_e32 v155, 3, v13
	v_and_b32_e32 v153, 15, v152
	s_cmpk_gt_i32 s40, 0x7f
	v_and_b32_e32 v3, 24, v3
	s_waitcnt lgkmcnt(0)
	s_barrier
	s_cbranch_scc1 .LBB0_1387
	v_add_u32_e32 v4, 0x2000, v4
	v_ashrrev_i32_e32 v5, 31, v4
	v_lshrrev_b32_e32 v5, 22, v5
	v_add_u32_e32 v5, v4, v5
	v_ashrrev_i32_e32 v15, 10, v5
	v_mul_i32_i24_e32 v5, 0x400, v15
	v_sub_u32_e32 v4, v4, v5
	v_lshrrev_b32_e32 v5, 4, v4
	v_bitop3_b32 v4, v5, v4, 32 bitop3:0x6c
	v_ashrrev_i32_e32 v5, 31, v4
	v_lshrrev_b32_e32 v5, 26, v5
	v_add_u32_e32 v5, v4, v5
	v_lshlrev_b32_e32 v6, 3, v15
	v_ashrrev_i32_e32 v16, 6, v5
	v_and_b32_e32 v6, -16, v6
	s_lshr_b32 s12, s40, 29
	v_add_u32_e32 v6, v16, v6
	s_add_i32 s12, s40, s12
	v_lshrrev_b32_e32 v7, 2, v6
	v_lshlrev_b32_e32 v9, 1, v6
	v_and_b32_e32 v5, 0xc0, v5
	s_and_b32 s13, s12, -8
	v_and_b32_e32 v7, 4, v7
	v_and_b32_e32 v8, 3, v16
	v_and_b32_e32 v9, 0x1fffd8, v9
	v_sub_u32_e32 v4, v4, v5
	s_lshl_b32 s43, s27, 3
	s_sub_i32 s13, s40, s13
	v_or3_b32 v7, v8, v7, v9
	v_lshlrev_b32_e32 v8, 5, v15
	v_ashrrev_i16_sdwa v4, v205, sext(v4) dst_sel:DWORD dst_unused:UNUSED_PAD src0_sel:DWORD src1_sel:BYTE_0
	s_add_i32 s28, s43, s13
	s_ashr_i32 s12, s12, 3
	s_ashr_i32 s15, s14, 6
	v_and_b32_e32 v8, 32, v8
	v_bfe_i32 v17, v4, 0, 16
	s_sub_i32 s34, 15, s12
	s_ashr_i32 s29, s28, 31
	s_ashr_i32 s16, s14, 8
	s_lshl_b32 s42, s15, 10
	v_add_lshl_u32 v4, v8, v17, 1
	s_lshl_b64 s[12:13], s[28:29], 19
	s_lshl_b64 s[18:19], s[34:35], 19
	v_lshl_add_u32 v134, v7, 11, v4
	v_lshl_add_u32 v136, v6, 11, v4
	v_and_b32_e32 v4, 0x1fffd8, v156
	s_lshr_b32 s85, s40, 3
	s_add_i32 s85, s85, s40
	s_and_b32 s85, s85, 3
	s_lshl_b32 s85, s85, 8
	s_add_i32 s84, s85, 0x100
	s_add_u32 s36, s10, s18
	v_or3_b32 v4, v155, v4, v154
	v_lshlrev_b32_e32 v5, 1, v132
	s_addc_u32 s37, s11, s19
	s_add_u32 s36, s36, s85
	s_addc_u32 s37, s37, 0
	s_add_i32 s29, s42, 0
	v_lshl_add_u32 v138, v4, 11, v5
	s_add_i32 m0, s29, 0x10000
	v_lshl_add_u32 v140, v133, 11, v5
	global_load_lds_dwordx4 v138, s[36:37]
	s_add_i32 m0, s29, 0x12000
	s_add_u32 s18, s36, 0x10000
	global_load_lds_dwordx4 v134, s[36:37]
	s_addc_u32 s19, s37, 0
	s_add_i32 m0, s29, 0x14000
	v_mov_b32_e32 v139, v2
	global_load_lds_dwordx4 v138, s[18:19]
	s_add_i32 m0, s29, 0x16000
	s_add_u32 s30, s6, s12
	s_addc_u32 s31, s7, s13
	s_add_u32 s30, s30, s85
	s_addc_u32 s31, s31, 0
	s_add_i32 s54, s29, 0x2000
	global_load_lds_dwordx4 v134, s[18:19]
	s_mov_b32 m0, s29
	s_add_u32 s12, s30, 0x40000
	global_load_lds_dwordx4 v140, s[30:31]
	s_mov_b32 m0, s54
	s_addc_u32 s13, s31, 0
	s_add_i32 s55, s29, 0x4000
	global_load_lds_dwordx4 v136, s[30:31]
	s_mov_b32 m0, s55
	s_add_i32 s62, s29, 0x6000
	global_load_lds_dwordx4 v140, s[12:13]
	s_mov_b32 m0, s62
	v_mov_b32_e32 v135, v2
	global_load_lds_dwordx4 v136, s[12:13]
	v_mov_b32_e32 v141, v2
	v_mov_b32_e32 v137, v2
	s_cmp_eq_u32 s16, 1
	v_lshl_add_u64 v[10:11], s[36:37], 0, v[138:139]
	v_lshl_add_u64 v[8:9], s[36:37], 0, v[134:135]
	v_lshl_add_u64 v[4:5], s[30:31], 0, v[140:141]
	s_cselect_b64 s[12:13], -1, 0
	s_cmp_lg_u32 s16, 1
	v_lshl_add_u64 v[6:7], s[30:31], 0, v[136:137]
	s_cbranch_scc1 .LBB0_1374
	s_nop 0
.LBB0_1374:
	v_lshlrev_b32_e32 v18, 1, v3
	v_lshlrev_b32_e32 v19, 2, v153
	s_and_b32 s17, s15, 3
	v_lshl_or_b32 v18, v153, 6, v18
	s_lshl_b32 s15, s16, 13
	v_and_b32_e32 v20, 32, v19
	s_add_i32 m0, s29, 0x18000
	v_lshl_add_u64 v[10:11], v[10:11], 0, s[52:53]
	v_bitop3_b32 v21, v18, s15, v20 bitop3:0xde
	s_lshl_b32 s15, s17, 12
	s_nop 0
	s_nop 0
	global_load_lds_dwordx4 v[10:11], off
	v_lshl_add_u64 v[8:9], v[8:9], 0, s[52:53]
	s_add_i32 m0, s29, 0x1a000
	s_add_i32 s63, s29, 0x8000
	s_add_i32 s64, s29, 0xa000
	global_load_lds_dwordx4 v[8:9], off
	v_lshl_add_u64 v[4:5], v[4:5], 0, s[52:53]
	s_mov_b32 m0, s63
	s_add_u32 s18, s36, 0x10080
	global_load_lds_dwordx4 v[4:5], off
	v_lshl_add_u64 v[4:5], v[6:7], 0, s[52:53]
	s_mov_b32 m0, s64
	s_addc_u32 s19, s37, 0
	global_load_lds_dwordx4 v[4:5], off
	s_add_i32 m0, s29, 0x1c000
	v_lshl_add_u64 v[4:5], s[18:19], 0, v[138:139]
	global_load_lds_dwordx4 v[4:5], off
	v_lshl_add_u64 v[4:5], s[18:19], 0, v[134:135]
	s_add_i32 m0, s29, 0x1e000
	s_cmpk_lt_u32 s14, 0x100
	global_load_lds_dwordx4 v[4:5], off
	v_cmp_lt_u32_e32 vcc, 7, v153
	v_bitop3_b32 v158, s15, v18, v20 bitop3:0xf6
	s_cselect_b64 s[14:15], -1, 0
	s_lshl_b32 s17, s17, 6
	v_cndmask_b32_e64 v4, 0, 32, vcc
	v_or3_b32 v162, s17, v4, v3
	v_lshlrev_b32_e32 v4, 14, v12
	v_and_b32_e32 v4, 0xffff8000, v4
	v_lshl_add_u32 v4, v13, 11, v4
	v_and_b32_e32 v5, 1, v12
	v_lshl_or_b32 v4, v5, 6, v4
	v_lshl_add_u32 v142, v14, 1, v4
	v_lshlrev_b32_e32 v4, 14, v15
	v_lshl_or_b32 v157, s16, 6, v153
	s_lshl_b32 s16, s16, 8
	v_and_b32_e32 v4, 0xffff8000, v4
	s_cmp_lg_u32 s12, 0
	s_cbranch_scc0 .Lpd5
	s_barrier
.Lpd5:
	s_waitcnt vmcnt(8)
	s_barrier
	s_waitcnt vmcnt(6)
	s_add_i32 s16, s16, 0
	v_lshl_add_u32 v4, v16, 11, v4
	v_and_b32_e32 v5, 1, v15
	s_add_i32 s16, s16, 0x20000
	v_lshl_or_b32 v4, v5, 6, v4
	s_mov_b32 s65, 0
	v_cndmask_b32_e64 v159, 0, -8, vcc
	v_cndmask_b32_e64 v160, 8, 0, vcc
	v_add_u32_e32 v161, s16, v19
	v_mov_b32_e32 v143, v2
	v_lshl_add_u32 v144, v17, 1, v4
	v_mov_b32_e32 v145, v2
	v_add_u32_e32 v163, 0, v21
	s_barrier
	s_sub_u32 s36, s36, s85
	s_subb_u32 s37, s37, 0
	s_sub_u32 s30, s30, s85
	s_subb_u32 s31, s31, 0
	s_branch .LBB0_1377

; #define PG8_WAIT_V(n) asm volatile("s_waitcnt vmcnt(" #n ")" ::: "memory")
; #define PG8_BAR __builtin_amdgcn_s_barrier()
;     DI void init_issue(u32x4 (&w)[R8::HAS_PRE ? 16 : 1], const Unit& u, int wr, int wc, int fr, int fq) const {
;     ...
;             const int row0 = u.pm * BM + wr * 64 + fr, col0 = u.pn * BM + (PERM ? wc * 64 : wc * 32) + 8 * fq;
; #pragma unroll
;             for (int ai = 0; ai < 2; ++ai)
; #pragma unroll
;                 for (int m = 0; m < 4; ++m)
; #pragma unroll
;                     for (int bj = 0; bj < 2; ++bj) w[(ai * 4 + m) * 2 + bj] = e.pre(row0 + ai * HALF + m * 16, col0 + bj * (PERM ? 32 : HALF));
; template <class Epi, class Sched, bool ALIGN_EPI = false, bool SP2 = false>
; __device__ __forceinline__ void gemm_phase(PG8_LAS unsigned char* lds, const Gemm g, const Sched& S, const Epi& E, const int tid) {
;     ...
;     for (int i = 0; i < 2; ++i) { int R, C; stage_rc(tid * 16 + i * 8192, R, C); const int Rb = Epi::PERM ? (2 * (R & ~31) + perm32(R & 31)) : R;
;         voffA[i] = (unsigned)(R * K + C) * 2u; voffB[i] = (unsigned)(Rb * K + C) * 2u; }
;     const size_t kstep = (size_t)(BK * 2);
;     const size_t hstep = (size_t)HALF * K * 2;
;     const size_t tstep = 2 * hstep;
;     const size_t hstepB = Epi::PERM ? (size_t)32 * K * 2 : hstep;
;     const unsigned ldsw = (unsigned)wid * 1024u;
;     const int aoff = lds_byte(wr * 64 + fr, fq * 8), boff = lds_byte(wc * 32 + fr, fq * 8);
;     ...
;     Unit cur, nxt; int ui = 0;
;     if (!S.next(0, cur)) return;
;     f32x4 acc[2][2][4][2];
;     u32x4 iw_[Epi::HAS_INIT ? 16 : 1];
;     if constexpr (Epi::HAS_INIT) E.init_issue(iw_, cur, wr, wc, fr, fq);
;     else {
; #pragma unroll
;     for (int a = 0; a < 2; ++a)
; #pragma unroll
;         for (int b = 0; b < 2; ++b)
; #pragma unroll
;             for (int m = 0; m < 4; ++m)
; #pragma unroll
;                 for (int n = 0; n < 2; ++n) acc[a][b][m][n] = (f32x4){0.f, 0.f, 0.f, 0.f};
;     }
;     bf16x8 At[4][2], B0[2][2], B1[2][2];
;     const char* cA = (const char*)g.A + (size_t)cur.pm * tstep; const char* cB = (const char*)g.Bt + (size_t)cur.pn * tstep;
;     S.a_ready(cur);
;     if constexpr (SP2) {
;         PG8_STAGE(PG8_SB(0, 0), cB, voffB); PG8_STAGE(PG8_SB(0, 1), cB + hstepB, voffB); PG8_STAGE(PG8_SA(0, 0), cA, voffA); PG8_STAGE(PG8_SA(0, 1), cA + hstep, voffA);
;         if (wr == 1) PG8_BAR;
;         PG8_WAIT_V(2); PG8_BAR;
.LBB0_1451:
	v_ashrrev_i32_e32 v5, 31, v3
	v_lshrrev_b32_e32 v5, 26, v5
	v_add_u32_e32 v5, v3, v5
	v_ashrrev_i32_e32 v142, 6, v5
	v_bfe_i32 v5, v3, 27, 1
	v_lshlrev_b32_e32 v4, 4, v3
	v_lshrrev_b32_e32 v5, 22, v5
	v_add_u32_e32 v5, v4, v5
	v_and_b32_e32 v5, 0xfffffc00, v5
	s_ashr_i32 s42, s14, 6
	v_sub_u32_e32 v5, v4, v5
	s_waitcnt lgkmcnt(0)
	s_add_u32 s0, s12, s0
	v_lshrrev_b32_e32 v6, 4, v5
	s_addc_u32 s1, s13, s1
	v_bitop3_b32 v5, v6, v5, 32 bitop3:0x6c
	s_add_u32 s10, s0, 0x4100000
	v_ashrrev_i32_e32 v7, 31, v5
	s_addc_u32 s11, s1, 0
	v_lshrrev_b32_e32 v7, 26, v7
	s_add_u32 s6, s12, 0x17100000
	v_add_u32_e32 v7, v5, v7
	s_addc_u32 s7, s13, 0
	v_lshlrev_b32_e32 v6, 3, v142
	v_ashrrev_i32_e32 v143, 6, v7
	v_and_b32_e32 v7, 0xc0, v7
	s_add_u32 s8, s12, 0xc300000
	v_and_b32_e32 v6, -16, v6
	v_sub_u32_e32 v5, v5, v7
	s_addc_u32 s9, s13, 0
	v_add_u32_e32 v133, v143, v6
	v_lshlrev_b32_e32 v6, 5, v142
	v_ashrrev_i16_sdwa v5, v205, sext(v5) dst_sel:DWORD dst_unused:UNUSED_PAD src0_sel:DWORD src1_sel:BYTE_0
	s_add_u32 s0, s12, 0x2e200000
	v_and_b32_e32 v6, 32, v6
	v_bfe_i32 v144, v5, 0, 16
	v_lshrrev_b32_e32 v5, 2, v133
	s_addc_u32 s1, s13, 0
	v_add_u32_e32 v132, v6, v144
	v_lshlrev_b32_e32 v155, 1, v133
	v_and_b32_e32 v153, 4, v5
	v_and_b32_e32 v154, 3, v143
	v_and_b32_e32 v152, 15, v3
	s_andn2_b64 vcc, exec, s[4:5]
	s_lshl_b32 s43, s42, 10
	s_cbranch_vccnz .LBB0_1499
	v_and_b32_e32 v5, 0x7ffd8, v155
	v_or3_b32 v5, v154, v5, v153
	v_lshlrev_b32_e32 v6, 1, v132
	v_add_u32_e32 v4, 0x2000, v4
	v_lshl_add_u32 v136, v5, 13, v6
	v_ashrrev_i32_e32 v5, 31, v4
	v_lshrrev_b32_e32 v5, 22, v5
	v_add_u32_e32 v5, v4, v5
	v_ashrrev_i32_e32 v145, 10, v5
	v_mul_i32_i24_e32 v5, 0x400, v145
	v_sub_u32_e32 v4, v4, v5
	v_lshrrev_b32_e32 v5, 4, v4
	v_bitop3_b32 v4, v5, v4, 32 bitop3:0x6c
	v_lshl_add_u32 v134, v133, 13, v6
	v_ashrrev_i32_e32 v6, 31, v4
	v_lshrrev_b32_e32 v6, 26, v6
	v_add_u32_e32 v6, v4, v6
	v_lshlrev_b32_e32 v5, 3, v145
	v_ashrrev_i32_e32 v147, 6, v6
	v_and_b32_e32 v6, 0xc0, v6
	v_and_b32_e32 v5, -16, v5
	v_sub_u32_e32 v4, v4, v6
	v_add_u32_e32 v5, v147, v5
	v_ashrrev_i16_sdwa v4, v205, sext(v4) dst_sel:DWORD dst_unused:UNUSED_PAD src0_sel:DWORD src1_sel:BYTE_0
	v_lshlrev_b32_e32 v7, 5, v145
	v_bfe_i32 v148, v4, 0, 16
	v_lshlrev_b32_e32 v4, 1, v5
	v_lshrrev_b32_e32 v6, 2, v5
	s_ashr_i32 s5, s14, 8
	v_and_b32_e32 v7, 32, v7
	v_and_b32_e32 v6, 4, v6
	v_and_b32_e32 v8, 3, v147
	v_and_b32_e32 v4, 0x7ffd8, v4
	s_lshl_b32 s15, s5, 6
	s_lshl_b32 s12, s28, 8
	s_and_b32 s4, s42, 3
	v_or3_b32 v4, v8, v6, v4
	v_add_lshl_u32 v6, v7, v148, 1
	s_add_i32 s12, s12, s15
	v_bfe_u32 v146, v3, 4, 2
	v_lshl_add_u32 v140, v4, 13, v6
	v_or_b32_e32 v4, s12, v152
	s_lshl_b32 s12, s24, 8
	s_lshl_b32 s54, s4, 6
	v_lshlrev_b32_e32 v156, 3, v146
	s_or_b32 s12, s12, s54
	v_or_b32_e32 v10, 16, v4
	v_lshl_add_u32 v138, v5, 13, v6
	v_or_b32_e32 v6, s12, v156
	v_ashrrev_i32_e32 v5, 31, v4
	v_ashrrev_i32_e32 v11, 31, v10
	v_lshlrev_b64 v[8:9], 11, v[4:5]
	v_ashrrev_i32_e32 v7, 31, v6
	v_lshlrev_b64 v[10:11], 11, v[10:11]
	v_lshl_add_u64 v[8:9], s[8:9], 0, v[8:9]
	v_lshlrev_b64 v[6:7], 1, v[6:7]
	v_lshl_add_u64 v[10:11], s[8:9], 0, v[10:11]
	v_lshl_add_u64 v[8:9], v[8:9], 0, v[6:7]
	v_lshl_add_u64 v[10:11], v[10:11], 0, v[6:7]
	global_load_dwordx4 v[64:67], v[8:9], off
	global_load_dwordx4 v[56:59], v[8:9], off offset:64
	global_load_dwordx4 v[60:63], v[10:11], off
	global_load_dwordx4 v[48:51], v[10:11], off offset:64
	v_or_b32_e32 v10, 32, v4
	v_or_b32_e32 v4, 48, v4
	v_ashrrev_i32_e32 v11, 31, v10
	v_ashrrev_i32_e32 v5, 31, v4
	v_lshlrev_b64 v[10:11], 11, v[10:11]
	v_lshlrev_b64 v[4:5], 11, v[4:5]
	v_lshl_add_u64 v[10:11], s[8:9], 0, v[10:11]
	v_lshl_add_u64 v[4:5], s[8:9], 0, v[4:5]
	v_lshl_add_u64 v[10:11], v[10:11], 0, v[6:7]
	v_lshl_add_u64 v[4:5], v[4:5], 0, v[6:7]
	v_add_co_u32_e32 v6, vcc, s57, v8
	global_load_dwordx4 v[52:55], v[10:11], off
	global_load_dwordx4 v[40:43], v[10:11], off offset:64
	v_addc_co_u32_e32 v7, vcc, 0, v9, vcc
	global_load_dwordx4 v[44:47], v[4:5], off
	global_load_dwordx4 v[36:39], v[4:5], off offset:64
	v_lshl_add_u64 v[4:5], v[8:9], 0, s[50:51]
	global_load_dwordx4 v[32:35], v[6:7], off
	global_load_dwordx4 v[28:31], v[4:5], off offset:64
	v_add_co_u32_e32 v6, vcc, s26, v8
	s_mov_b32 s12, 0x50000
	s_nop 0
	v_addc_co_u32_e32 v7, vcc, 0, v9, vcc
	v_lshl_add_u64 v[4:5], v[8:9], 0, s[72:73]
	global_load_dwordx4 v[24:27], v[6:7], off
	global_load_dwordx4 v[20:23], v[4:5], off offset:64
	v_add_co_u32_e32 v6, vcc, s12, v8
	s_mov_b64 s[12:13], 0x58000
	s_nop 0
	v_addc_co_u32_e32 v7, vcc, 0, v9, vcc
	v_lshl_add_u64 v[16:17], v[8:9], 0, s[12:13]
	s_mov_b32 s12, 0x58000
	s_ashr_i32 s29, s28, 31
	s_ashr_i32 s25, s24, 31
	v_lshl_add_u64 v[4:5], v[8:9], 0, s[74:75]
	v_add_co_u32_e32 v8, vcc, s12, v8
	s_lshl_b64 s[12:13], s[28:29], 21
	s_lshl_b64 s[16:17], s[24:25], 21
	s_add_u32 s36, s10, s16
	s_addc_u32 s37, s11, s17
	s_add_i32 s29, s43, 0
	v_addc_co_u32_e32 v9, vcc, 0, v9, vcc
	s_add_i32 m0, s29, 0x10000
	global_load_dwordx4 v[12:15], v[6:7], off
	s_nop 0
	global_load_dwordx4 v[4:7], v[4:5], off offset:64
	s_nop 0
	global_load_dwordx4 v[8:11], v[8:9], off
	s_nop 0
	global_load_dwordx4 v[16:19], v[16:17], off offset:64
	v_mov_b32_e32 v137, v2
	global_load_lds_dwordx4 v136, s[36:37]
	s_add_i32 m0, s29, 0x12000
	s_add_u32 s16, s36, 0x40000
	global_load_lds_dwordx4 v140, s[36:37]
	s_addc_u32 s17, s37, 0
	s_add_i32 m0, s29, 0x14000
	v_mov_b32_e32 v141, v2
	global_load_lds_dwordx4 v136, s[16:17]
	s_add_i32 m0, s29, 0x16000
	s_add_u32 s38, s6, s12
	s_addc_u32 s39, s7, s13
	s_add_i32 s55, s29, 0x2000
	global_load_lds_dwordx4 v140, s[16:17]
	s_mov_b32 m0, s29
	s_add_u32 s12, s38, 0x100000
	global_load_lds_dwordx4 v134, s[38:39]
	s_mov_b32 m0, s55
	s_addc_u32 s13, s39, 0
	s_add_i32 s62, s29, 0x4000
	global_load_lds_dwordx4 v138, s[38:39]
	s_mov_b32 m0, s62
	s_add_i32 s63, s29, 0x6000
	global_load_lds_dwordx4 v134, s[12:13]
	s_mov_b32 m0, s63
	v_mov_b32_e32 v135, v2
	global_load_lds_dwordx4 v138, s[12:13]
	v_mov_b32_e32 v139, v2
	s_cmp_eq_u32 s5, 1
	v_lshl_add_u64 v[74:75], s[36:37], 0, v[136:137]
	v_lshl_add_u64 v[72:73], s[36:37], 0, v[140:141]
	v_lshl_add_u64 v[68:69], s[38:39], 0, v[134:135]
	s_cselect_b64 s[12:13], -1, 0
	s_cmp_lg_u32 s5, 1
	v_lshl_add_u64 v[70:71], s[38:39], 0, v[138:139]
	s_cbranch_scc1 .LBB0_1454
	s_nop 0
; DI float bf_lo(unsigned u) { return __uint_as_float(u << 16); }
; DI float bf_hi(unsigned u) { return __uint_as_float(u & 0xffff0000u); }
; #define PG8_STAGE(bufoff, gbase, voff) do { _Pragma("unroll") for (int _i = 0; _i < 2; ++_i) \
;         __builtin_amdgcn_global_load_lds((const unsigned*)((const char*)(gbase) + (voff)[_i]), (PG8_LAS unsigned*)(lds + (bufoff) + ldsw + _i * 8192), 16, 0, 0); } while (0)
; #define PG8_WAIT_V(n) asm volatile("s_waitcnt vmcnt(" #n ")" ::: "memory")
; #define PG8_BAR __builtin_amdgcn_s_barrier()
;     DI void init_finish(f32x4 (&acc)[2][2][4][2], const u32x4 (&w)[R8::HAS_PRE ? 16 : 1]) const {
;     ...
; #pragma unroll
;             for (int ai = 0; ai < 2; ++ai)
; #pragma unroll
;                 for (int m = 0; m < 4; ++m)
; #pragma unroll
;                     for (int bj = 0; bj < 2; ++bj) { const u32x4 v = w[(ai * 4 + m) * 2 + bj];
;                         acc[ai][bj][m][0] = (f32x4){bf_lo(v.x), bf_hi(v.x), bf_lo(v.y), bf_hi(v.y)}; acc[ai][bj][m][1] = (f32x4){bf_lo(v.z), bf_hi(v.z), bf_lo(v.w), bf_hi(v.w)}; }
; template <class Epi, class Sched, bool ALIGN_EPI = false, bool SP2 = false>
; __device__ __forceinline__ void gemm_phase(PG8_LAS unsigned char* lds, const Gemm g, const Sched& S, const Epi& E, const int tid) {
;     ...
;         if (wr == 1) PG8_BAR;
;         PG8_WAIT_V(2); PG8_BAR;
;         PG8_STAGE(PG8_SB(1, 0), cB + kstep, voffB); PG8_STAGE(PG8_SA(1, 0), cA + kstep, voffA); PG8_STAGE(PG8_SB(1, 1), cB + hstepB + kstep, voffB);
;         PG8_WAIT_V(6); PG8_BAR;
;     } else {
;         PG8_STAGE(PG8_SB(0, 0), cB, voffB); PG8_STAGE(PG8_SA(0, 0), cA, voffA); PG8_STAGE(PG8_SB(0, 1), cB + hstepB, voffB); PG8_STAGE(PG8_SA(0, 1), cA + hstep, voffA);
;         if (wr == 1) PG8_BAR;
;         PG8_WAIT_V(4); PG8_BAR;
;         PG8_STAGE(PG8_SB(1, 0), cB + kstep, voffB); PG8_STAGE(PG8_SA(1, 0), cA + kstep, voffA); PG8_STAGE(PG8_SB(1, 1), cB + hstepB + kstep, voffB);
;         PG8_WAIT_V(6); PG8_BAR;
;     }
;     if constexpr (Epi::HAS_INIT) E.init_finish(acc, iw_);
.LBB0_1454:
	v_or_b32_e32 v157, s15, v152
	v_lshlrev_b32_e32 v76, 6, v157
	v_lshlrev_b32_e32 v77, 4, v146
	s_movk_i32 s15, 0x3c0
	v_lshlrev_b32_e32 v78, 2, v157
	v_and_or_b32 v76, v76, s15, v77
	s_lshl_b32 s5, s5, 13
	v_and_b32_e32 v78, 32, v78
	v_bitop3_b32 v149, v76, s5, v78 bitop3:0xde
	v_lshl_or_b32 v76, v152, 6, v77
	v_lshlrev_b32_e32 v77, 2, v152
	s_add_i32 m0, s29, 0x18000
	v_lshl_add_u64 v[74:75], v[74:75], 0, s[52:53]
	s_lshl_b32 s4, s4, 12
	v_and_b32_e32 v77, 32, v77
	s_nop 0
	s_nop 0
	global_load_lds_dwordx4 v[74:75], off
	v_lshl_add_u64 v[72:73], v[72:73], 0, s[52:53]
	s_add_i32 m0, s29, 0x1a000
	s_add_i32 s64, s29, 0x8000
	s_add_i32 s65, s29, 0xa000
	v_bitop3_b32 v158, v76, s4, v77 bitop3:0xde
	global_load_lds_dwordx4 v[72:73], off
	v_lshl_add_u64 v[68:69], v[68:69], 0, s[52:53]
	s_mov_b32 m0, s64
	s_add_u32 s4, s36, 0x40080
	global_load_lds_dwordx4 v[68:69], off
	v_lshl_add_u64 v[68:69], v[70:71], 0, s[52:53]
	s_mov_b32 m0, s65
	s_addc_u32 s5, s37, 0
	global_load_lds_dwordx4 v[68:69], off
	s_add_i32 m0, s29, 0x1c000
	v_lshl_add_u64 v[68:69], s[4:5], 0, v[136:137]
	global_load_lds_dwordx4 v[68:69], off
	v_lshl_add_u64 v[68:69], s[4:5], 0, v[140:141]
	s_add_i32 m0, s29, 0x1e000
	v_cmp_eq_u32_e64 s[4:5], 0, v146
	global_load_lds_dwordx4 v[68:69], off
	v_lshlrev_b32_e32 v146, 16, v142
	v_and_b32_e32 v146, 0xfffe0000, v146
	v_lshl_add_u32 v143, v143, 13, v146
	v_and_b32_e32 v142, 1, v142
	v_lshl_or_b32 v142, v142, 6, v143
	v_lshl_add_u32 v142, v144, 1, v142
	v_lshlrev_b32_e32 v144, 16, v145
	v_and_b32_e32 v144, 0xfffe0000, v144
	s_cmp_lg_u32 s12, 0
	s_cbranch_scc0 .Lpd6
	s_barrier
.Lpd6:
	s_waitcnt vmcnt(8)
	s_barrier
	s_waitcnt vmcnt(6)
	v_lshl_add_u32 v144, v147, 13, v144
	v_and_b32_e32 v145, 1, v145
	s_cmpk_lt_u32 s14, 0x100
	v_lshl_or_b32 v144, v145, 6, v144
	s_waitcnt vmcnt(0)
	v_lshlrev_b32_e32 v120, 16, v64
	v_and_b32_e32 v121, 0xffff0000, v64
	v_lshlrev_b32_e32 v122, 16, v65
	v_and_b32_e32 v123, 0xffff0000, v65
	v_lshlrev_b32_e32 v128, 16, v66
	v_and_b32_e32 v129, 0xffff0000, v66
	v_lshlrev_b32_e32 v130, 16, v67
	v_and_b32_e32 v131, 0xffff0000, v67
	v_lshlrev_b32_e32 v116, 16, v56
	v_and_b32_e32 v117, 0xffff0000, v56
	v_lshlrev_b32_e32 v118, 16, v57
	v_and_b32_e32 v119, 0xffff0000, v57
	v_lshlrev_b32_e32 v124, 16, v58
	v_and_b32_e32 v125, 0xffff0000, v58
	v_lshlrev_b32_e32 v126, 16, v59
	v_and_b32_e32 v127, 0xffff0000, v59
	v_lshlrev_b32_e32 v100, 16, v60
	v_and_b32_e32 v101, 0xffff0000, v60
	v_lshlrev_b32_e32 v102, 16, v61
	v_and_b32_e32 v103, 0xffff0000, v61
	v_lshlrev_b32_e32 v108, 16, v62
	v_and_b32_e32 v109, 0xffff0000, v62
	v_lshlrev_b32_e32 v110, 16, v63
	v_and_b32_e32 v111, 0xffff0000, v63
	v_lshlrev_b32_e32 v104, 16, v48
	v_and_b32_e32 v105, 0xffff0000, v48
	v_lshlrev_b32_e32 v106, 16, v49
	v_and_b32_e32 v107, 0xffff0000, v49
	v_lshlrev_b32_e32 v112, 16, v50
	v_and_b32_e32 v113, 0xffff0000, v50
	v_lshlrev_b32_e32 v114, 16, v51
	v_and_b32_e32 v115, 0xffff0000, v51
	v_lshlrev_b32_e32 v84, 16, v52
	v_and_b32_e32 v85, 0xffff0000, v52
	v_lshlrev_b32_e32 v86, 16, v53
	v_and_b32_e32 v87, 0xffff0000, v53
	v_lshlrev_b32_e32 v92, 16, v54
	v_and_b32_e32 v93, 0xffff0000, v54
	v_lshlrev_b32_e32 v94, 16, v55
	v_and_b32_e32 v95, 0xffff0000, v55
	v_lshlrev_b32_e32 v88, 16, v40
	v_and_b32_e32 v89, 0xffff0000, v40
	v_lshlrev_b32_e32 v90, 16, v41
	v_and_b32_e32 v91, 0xffff0000, v41
	v_lshlrev_b32_e32 v96, 16, v42
	v_and_b32_e32 v97, 0xffff0000, v42
	v_lshlrev_b32_e32 v98, 16, v43
	v_and_b32_e32 v99, 0xffff0000, v43
	v_lshlrev_b32_e32 v68, 16, v44
	v_and_b32_e32 v69, 0xffff0000, v44
	v_lshlrev_b32_e32 v70, 16, v45
	v_and_b32_e32 v71, 0xffff0000, v45
	v_lshlrev_b32_e32 v76, 16, v46
	v_and_b32_e32 v77, 0xffff0000, v46
	v_lshlrev_b32_e32 v78, 16, v47
	v_and_b32_e32 v79, 0xffff0000, v47
	v_lshlrev_b32_e32 v72, 16, v36
	v_and_b32_e32 v73, 0xffff0000, v36
	v_lshlrev_b32_e32 v74, 16, v37
	v_and_b32_e32 v75, 0xffff0000, v37
	v_lshlrev_b32_e32 v80, 16, v38
	v_and_b32_e32 v81, 0xffff0000, v38
	v_lshlrev_b32_e32 v82, 16, v39
	v_and_b32_e32 v83, 0xffff0000, v39
	v_lshlrev_b32_e32 v52, 16, v32
	v_and_b32_e32 v53, 0xffff0000, v32
	v_lshlrev_b32_e32 v54, 16, v33
	v_and_b32_e32 v55, 0xffff0000, v33
	v_lshlrev_b32_e32 v60, 16, v34
	v_and_b32_e32 v61, 0xffff0000, v34
	v_lshlrev_b32_e32 v62, 16, v35
	v_and_b32_e32 v63, 0xffff0000, v35
	v_lshlrev_b32_e32 v56, 16, v28
	v_and_b32_e32 v57, 0xffff0000, v28
	v_lshlrev_b32_e32 v58, 16, v29
	v_and_b32_e32 v59, 0xffff0000, v29
	v_lshlrev_b32_e32 v64, 16, v30
	v_and_b32_e32 v65, 0xffff0000, v30
	v_lshlrev_b32_e32 v66, 16, v31
	v_and_b32_e32 v67, 0xffff0000, v31
	v_lshlrev_b32_e32 v36, 16, v24
	v_and_b32_e32 v37, 0xffff0000, v24
	v_lshlrev_b32_e32 v38, 16, v25
	v_and_b32_e32 v39, 0xffff0000, v25
	v_lshlrev_b32_e32 v44, 16, v26
	v_and_b32_e32 v45, 0xffff0000, v26
	v_lshlrev_b32_e32 v46, 16, v27
	v_and_b32_e32 v47, 0xffff0000, v27
	v_lshlrev_b32_e32 v40, 16, v20
	v_and_b32_e32 v41, 0xffff0000, v20
	v_lshlrev_b32_e32 v42, 16, v21
	v_and_b32_e32 v43, 0xffff0000, v21
	v_lshlrev_b32_e32 v48, 16, v22
	v_and_b32_e32 v49, 0xffff0000, v22
	v_lshlrev_b32_e32 v50, 16, v23
	v_and_b32_e32 v51, 0xffff0000, v23
	v_lshlrev_b32_e32 v20, 16, v12
	v_and_b32_e32 v21, 0xffff0000, v12
	v_lshlrev_b32_e32 v22, 16, v13
	v_and_b32_e32 v23, 0xffff0000, v13
	v_lshlrev_b32_e32 v28, 16, v14
	v_and_b32_e32 v29, 0xffff0000, v14
	v_lshlrev_b32_e32 v30, 16, v15
	v_and_b32_e32 v31, 0xffff0000, v15
	v_lshlrev_b32_e32 v24, 16, v4
	v_and_b32_e32 v25, 0xffff0000, v4
	v_lshlrev_b32_e32 v26, 16, v5
	v_and_b32_e32 v27, 0xffff0000, v5
	v_lshlrev_b32_e32 v32, 16, v6
	v_and_b32_e32 v33, 0xffff0000, v6
	v_lshlrev_b32_e32 v34, 16, v7
	v_and_b32_e32 v35, 0xffff0000, v7
	v_lshlrev_b32_e32 v4, 16, v8
	v_and_b32_e32 v5, 0xffff0000, v8
	v_lshlrev_b32_e32 v6, 16, v9
	v_and_b32_e32 v7, 0xffff0000, v9
	v_lshlrev_b32_e32 v12, 16, v10
	v_and_b32_e32 v13, 0xffff0000, v10
	v_lshlrev_b32_e32 v14, 16, v11
	v_and_b32_e32 v15, 0xffff0000, v11
	v_lshlrev_b32_e32 v8, 16, v16
	v_and_b32_e32 v9, 0xffff0000, v16
	v_lshlrev_b32_e32 v10, 16, v17
	v_and_b32_e32 v11, 0xffff0000, v17
	v_lshlrev_b32_e32 v16, 16, v18
	v_and_b32_e32 v17, 0xffff0000, v18
	v_lshlrev_b32_e32 v18, 16, v19
	v_and_b32_e32 v19, 0xffff0000, v19
	s_cselect_b64 s[14:15], -1, 0
	s_mov_b32 s66, 0
	s_lshl_b32 s67, s27, 3
	v_or_b32_e32 v159, s54, v156
	v_mov_b32_e32 v143, v2
	v_lshl_add_u32 v144, v148, 1, v144
	v_mov_b32_e32 v145, v2
	v_add_u32_e32 v160, 0, v149
	s_barrier
	s_branch .LBB0_1457
